# up-projection rmsnorm pre-pass: all loads of a row issued first (unrolled), same accumulation order
# speedup vs baseline: 1.0015x; 1.0015x over previous
.LBB0_823:
	global_load_dwordx4 v[6:9], v[2:3], off offset:16
	global_load_dwordx4 v[10:13], v[2:3], off
	global_load_dwordx4 v[14:17], v[2:3], off offset:-16
	global_load_dwordx4 v[18:21], v[2:3], off offset:-32
	global_load_dwordx4 v[66:69], v[2:3], off offset:80
	global_load_dwordx4 v[70:73], v[2:3], off offset:64
	global_load_dwordx4 v[74:77], v[2:3], off offset:48
	global_load_dwordx4 v[78:81], v[2:3], off offset:32
	global_load_dwordx4 v[82:85], v[2:3], off offset:144
	global_load_dwordx4 v[86:89], v[2:3], off offset:128
	global_load_dwordx4 v[90:93], v[2:3], off offset:112
	global_load_dwordx4 v[94:97], v[2:3], off offset:96
	global_load_dwordx4 v[38:41], v[2:3], off offset:208
	global_load_dwordx4 v[42:45], v[2:3], off offset:192
	global_load_dwordx4 v[46:49], v[2:3], off offset:176
	global_load_dwordx4 v[50:53], v[2:3], off offset:160
	s_waitcnt vmcnt(12)
	v_lshlrev_b32_e32 v5, 16, v18
	v_lshlrev_b32_e32 v23, 16, v19
	v_and_b32_e32 v22, 0xffff0000, v18
	v_fmac_f32_e32 v4, v5, v5
	v_pk_mul_f32 v[22:23], v[22:23], v[22:23]
	v_lshlrev_b32_e32 v5, 16, v20
	v_add_f32_e32 v4, v22, v4
	v_add_f32_e32 v18, v23, v4
	v_and_b32_e32 v4, 0xffff0000, v19
	v_pk_mul_f32 v[4:5], v[4:5], v[4:5]
	s_nop 0
	v_add_f32_e32 v4, v4, v18
	v_add_f32_e32 v18, v5, v4
	v_lshlrev_b32_e32 v5, 16, v21
	v_and_b32_e32 v4, 0xffff0000, v20
	v_pk_mul_f32 v[4:5], v[4:5], v[4:5]
	s_nop 0
	v_add_f32_e32 v4, v4, v18
	v_add_f32_e32 v18, v5, v4
	v_and_b32_e32 v4, 0xffff0000, v21
	v_fmac_f32_e32 v18, v4, v4
	v_lshlrev_b32_e32 v4, 16, v14
	v_fmac_f32_e32 v18, v4, v4
	v_lshlrev_b32_e32 v5, 16, v15
	v_and_b32_e32 v4, 0xffff0000, v14
	v_pk_mul_f32 v[4:5], v[4:5], v[4:5]
	s_nop 0
	v_add_f32_e32 v4, v4, v18
	v_add_f32_e32 v14, v5, v4
	v_lshlrev_b32_e32 v5, 16, v16
	v_and_b32_e32 v4, 0xffff0000, v15
	v_pk_mul_f32 v[4:5], v[4:5], v[4:5]
	s_nop 0
	v_add_f32_e32 v4, v4, v14
	v_add_f32_e32 v14, v5, v4
	v_lshlrev_b32_e32 v5, 16, v17
	v_and_b32_e32 v4, 0xffff0000, v16
	v_pk_mul_f32 v[4:5], v[4:5], v[4:5]
	s_nop 0
	v_add_f32_e32 v4, v4, v14
	v_add_f32_e32 v14, v5, v4
	v_and_b32_e32 v4, 0xffff0000, v17
	v_fmac_f32_e32 v14, v4, v4
	v_lshlrev_b32_e32 v4, 16, v10
	v_fmac_f32_e32 v14, v4, v4
	v_lshlrev_b32_e32 v5, 16, v11
	v_and_b32_e32 v4, 0xffff0000, v10
	v_pk_mul_f32 v[4:5], v[4:5], v[4:5]
	s_nop 0
	v_add_f32_e32 v4, v4, v14
	v_add_f32_e32 v10, v5, v4
	v_lshlrev_b32_e32 v5, 16, v12
	v_and_b32_e32 v4, 0xffff0000, v11
	v_pk_mul_f32 v[4:5], v[4:5], v[4:5]
	s_nop 0
	v_add_f32_e32 v4, v4, v10
	v_add_f32_e32 v10, v5, v4
	v_lshlrev_b32_e32 v5, 16, v13
	v_and_b32_e32 v4, 0xffff0000, v12
	v_pk_mul_f32 v[4:5], v[4:5], v[4:5]
	s_nop 0
	v_add_f32_e32 v4, v4, v10
	v_add_f32_e32 v10, v5, v4
	v_and_b32_e32 v4, 0xffff0000, v13
	v_fmac_f32_e32 v10, v4, v4
	v_lshlrev_b32_e32 v4, 16, v6
	v_fmac_f32_e32 v10, v4, v4
	v_lshlrev_b32_e32 v5, 16, v7
	v_and_b32_e32 v4, 0xffff0000, v6
	v_pk_mul_f32 v[4:5], v[4:5], v[4:5]
	s_nop 0
	v_add_f32_e32 v4, v4, v10
	v_add_f32_e32 v6, v5, v4
	v_lshlrev_b32_e32 v5, 16, v8
	v_and_b32_e32 v4, 0xffff0000, v7
	v_pk_mul_f32 v[4:5], v[4:5], v[4:5]
	s_nop 0
	v_add_f32_e32 v4, v4, v6
	v_add_f32_e32 v6, v5, v4
	v_lshlrev_b32_e32 v5, 16, v9
	v_and_b32_e32 v4, 0xffff0000, v8
	v_pk_mul_f32 v[4:5], v[4:5], v[4:5]
	s_nop 0
	v_add_f32_e32 v4, v4, v6
	v_add_f32_e32 v4, v5, v4
	v_and_b32_e32 v5, 0xffff0000, v9
	v_fmac_f32_e32 v4, v5, v5
	s_waitcnt vmcnt(8)
	v_lshlrev_b32_e32 v5, 16, v78
	v_lshlrev_b32_e32 v23, 16, v79
	v_and_b32_e32 v22, 0xffff0000, v78
	v_fmac_f32_e32 v4, v5, v5
	v_pk_mul_f32 v[22:23], v[22:23], v[22:23]
	v_lshlrev_b32_e32 v5, 16, v80
	v_add_f32_e32 v4, v22, v4
	v_add_f32_e32 v78, v23, v4
	v_and_b32_e32 v4, 0xffff0000, v79
	v_pk_mul_f32 v[4:5], v[4:5], v[4:5]
	s_nop 0
	v_add_f32_e32 v4, v4, v78
	v_add_f32_e32 v78, v5, v4
	v_lshlrev_b32_e32 v5, 16, v81
	v_and_b32_e32 v4, 0xffff0000, v80
	v_pk_mul_f32 v[4:5], v[4:5], v[4:5]
	s_nop 0
	v_add_f32_e32 v4, v4, v78
	v_add_f32_e32 v78, v5, v4
	v_and_b32_e32 v4, 0xffff0000, v81
	v_fmac_f32_e32 v78, v4, v4
	v_lshlrev_b32_e32 v4, 16, v74
	v_fmac_f32_e32 v78, v4, v4
	v_lshlrev_b32_e32 v5, 16, v75
	v_and_b32_e32 v4, 0xffff0000, v74
	v_pk_mul_f32 v[4:5], v[4:5], v[4:5]
	s_nop 0
	v_add_f32_e32 v4, v4, v78
	v_add_f32_e32 v74, v5, v4
	v_lshlrev_b32_e32 v5, 16, v76
	v_and_b32_e32 v4, 0xffff0000, v75
	v_pk_mul_f32 v[4:5], v[4:5], v[4:5]
	s_nop 0
	v_add_f32_e32 v4, v4, v74
	v_add_f32_e32 v74, v5, v4
	v_lshlrev_b32_e32 v5, 16, v77
	v_and_b32_e32 v4, 0xffff0000, v76
	v_pk_mul_f32 v[4:5], v[4:5], v[4:5]
	s_nop 0
	v_add_f32_e32 v4, v4, v74
	v_add_f32_e32 v74, v5, v4
	v_and_b32_e32 v4, 0xffff0000, v77
	v_fmac_f32_e32 v74, v4, v4
	v_lshlrev_b32_e32 v4, 16, v70
	v_fmac_f32_e32 v74, v4, v4
	v_lshlrev_b32_e32 v5, 16, v71
	v_and_b32_e32 v4, 0xffff0000, v70
	v_pk_mul_f32 v[4:5], v[4:5], v[4:5]
	s_nop 0
	v_add_f32_e32 v4, v4, v74
	v_add_f32_e32 v70, v5, v4
	v_lshlrev_b32_e32 v5, 16, v72
	v_and_b32_e32 v4, 0xffff0000, v71
	v_pk_mul_f32 v[4:5], v[4:5], v[4:5]
	s_nop 0
	v_add_f32_e32 v4, v4, v70
	v_add_f32_e32 v70, v5, v4
	v_lshlrev_b32_e32 v5, 16, v73
	v_and_b32_e32 v4, 0xffff0000, v72
	v_pk_mul_f32 v[4:5], v[4:5], v[4:5]
	s_nop 0
	v_add_f32_e32 v4, v4, v70
	v_add_f32_e32 v70, v5, v4
	v_and_b32_e32 v4, 0xffff0000, v73
	v_fmac_f32_e32 v70, v4, v4
	v_lshlrev_b32_e32 v4, 16, v66
	v_fmac_f32_e32 v70, v4, v4
	v_lshlrev_b32_e32 v5, 16, v67
	v_and_b32_e32 v4, 0xffff0000, v66
	v_pk_mul_f32 v[4:5], v[4:5], v[4:5]
	s_nop 0
	v_add_f32_e32 v4, v4, v70
	v_add_f32_e32 v66, v5, v4
	v_lshlrev_b32_e32 v5, 16, v68
	v_and_b32_e32 v4, 0xffff0000, v67
	v_pk_mul_f32 v[4:5], v[4:5], v[4:5]
	s_nop 0
	v_add_f32_e32 v4, v4, v66
	v_add_f32_e32 v66, v5, v4
	v_lshlrev_b32_e32 v5, 16, v69
	v_and_b32_e32 v4, 0xffff0000, v68
	v_pk_mul_f32 v[4:5], v[4:5], v[4:5]
	s_nop 0
	v_add_f32_e32 v4, v4, v66
	v_add_f32_e32 v4, v5, v4
	v_and_b32_e32 v5, 0xffff0000, v69
	v_fmac_f32_e32 v4, v5, v5
	s_waitcnt vmcnt(4)
	v_lshlrev_b32_e32 v5, 16, v94
	v_lshlrev_b32_e32 v23, 16, v95
	v_and_b32_e32 v22, 0xffff0000, v94
	v_fmac_f32_e32 v4, v5, v5
	v_pk_mul_f32 v[22:23], v[22:23], v[22:23]
	v_lshlrev_b32_e32 v5, 16, v96
	v_add_f32_e32 v4, v22, v4
	v_add_f32_e32 v94, v23, v4
	v_and_b32_e32 v4, 0xffff0000, v95
	v_pk_mul_f32 v[4:5], v[4:5], v[4:5]
	s_nop 0
	v_add_f32_e32 v4, v4, v94
	v_add_f32_e32 v94, v5, v4
	v_lshlrev_b32_e32 v5, 16, v97
	v_and_b32_e32 v4, 0xffff0000, v96
	v_pk_mul_f32 v[4:5], v[4:5], v[4:5]
	s_nop 0
	v_add_f32_e32 v4, v4, v94
	v_add_f32_e32 v94, v5, v4
	v_and_b32_e32 v4, 0xffff0000, v97
	v_fmac_f32_e32 v94, v4, v4
	v_lshlrev_b32_e32 v4, 16, v90
	v_fmac_f32_e32 v94, v4, v4
	v_lshlrev_b32_e32 v5, 16, v91
	v_and_b32_e32 v4, 0xffff0000, v90
	v_pk_mul_f32 v[4:5], v[4:5], v[4:5]
	s_nop 0
	v_add_f32_e32 v4, v4, v94
	v_add_f32_e32 v90, v5, v4
	v_lshlrev_b32_e32 v5, 16, v92
	v_and_b32_e32 v4, 0xffff0000, v91
	v_pk_mul_f32 v[4:5], v[4:5], v[4:5]
	s_nop 0
	v_add_f32_e32 v4, v4, v90
	v_add_f32_e32 v90, v5, v4
	v_lshlrev_b32_e32 v5, 16, v93
	v_and_b32_e32 v4, 0xffff0000, v92
	v_pk_mul_f32 v[4:5], v[4:5], v[4:5]
	s_nop 0
	v_add_f32_e32 v4, v4, v90
	v_add_f32_e32 v90, v5, v4
	v_and_b32_e32 v4, 0xffff0000, v93
	v_fmac_f32_e32 v90, v4, v4
	v_lshlrev_b32_e32 v4, 16, v86
	v_fmac_f32_e32 v90, v4, v4
	v_lshlrev_b32_e32 v5, 16, v87
	v_and_b32_e32 v4, 0xffff0000, v86
	v_pk_mul_f32 v[4:5], v[4:5], v[4:5]
	s_nop 0
	v_add_f32_e32 v4, v4, v90
	v_add_f32_e32 v86, v5, v4
	v_lshlrev_b32_e32 v5, 16, v88
	v_and_b32_e32 v4, 0xffff0000, v87
	v_pk_mul_f32 v[4:5], v[4:5], v[4:5]
	s_nop 0
	v_add_f32_e32 v4, v4, v86
	v_add_f32_e32 v86, v5, v4
	v_lshlrev_b32_e32 v5, 16, v89
	v_and_b32_e32 v4, 0xffff0000, v88
	v_pk_mul_f32 v[4:5], v[4:5], v[4:5]
	s_nop 0
	v_add_f32_e32 v4, v4, v86
	v_add_f32_e32 v86, v5, v4
	v_and_b32_e32 v4, 0xffff0000, v89
	v_fmac_f32_e32 v86, v4, v4
	v_lshlrev_b32_e32 v4, 16, v82
	v_fmac_f32_e32 v86, v4, v4
	v_lshlrev_b32_e32 v5, 16, v83
	v_and_b32_e32 v4, 0xffff0000, v82
	v_pk_mul_f32 v[4:5], v[4:5], v[4:5]
	s_nop 0
	v_add_f32_e32 v4, v4, v86
	v_add_f32_e32 v82, v5, v4
	v_lshlrev_b32_e32 v5, 16, v84
	v_and_b32_e32 v4, 0xffff0000, v83
	v_pk_mul_f32 v[4:5], v[4:5], v[4:5]
	s_nop 0
	v_add_f32_e32 v4, v4, v82
	v_add_f32_e32 v82, v5, v4
	v_lshlrev_b32_e32 v5, 16, v85
	v_and_b32_e32 v4, 0xffff0000, v84
	v_pk_mul_f32 v[4:5], v[4:5], v[4:5]
	s_nop 0
	v_add_f32_e32 v4, v4, v82
	v_add_f32_e32 v4, v5, v4
	v_and_b32_e32 v5, 0xffff0000, v85
	v_fmac_f32_e32 v4, v5, v5
	s_waitcnt vmcnt(0)
	v_lshlrev_b32_e32 v5, 16, v50
	v_lshlrev_b32_e32 v23, 16, v51
	v_and_b32_e32 v22, 0xffff0000, v50
	v_fmac_f32_e32 v4, v5, v5
	v_pk_mul_f32 v[22:23], v[22:23], v[22:23]
	v_lshlrev_b32_e32 v5, 16, v52
	v_add_f32_e32 v4, v22, v4
	v_add_f32_e32 v50, v23, v4
	v_and_b32_e32 v4, 0xffff0000, v51
	v_pk_mul_f32 v[4:5], v[4:5], v[4:5]
	s_nop 0
	v_add_f32_e32 v4, v4, v50
	v_add_f32_e32 v50, v5, v4
	v_lshlrev_b32_e32 v5, 16, v53
	v_and_b32_e32 v4, 0xffff0000, v52
	v_pk_mul_f32 v[4:5], v[4:5], v[4:5]
	s_nop 0
	v_add_f32_e32 v4, v4, v50
	v_add_f32_e32 v50, v5, v4
	v_and_b32_e32 v4, 0xffff0000, v53
	v_fmac_f32_e32 v50, v4, v4
	v_lshlrev_b32_e32 v4, 16, v46
	v_fmac_f32_e32 v50, v4, v4
	v_lshlrev_b32_e32 v5, 16, v47
	v_and_b32_e32 v4, 0xffff0000, v46
	v_pk_mul_f32 v[4:5], v[4:5], v[4:5]
	s_nop 0
	v_add_f32_e32 v4, v4, v50
	v_add_f32_e32 v46, v5, v4
	v_lshlrev_b32_e32 v5, 16, v48
	v_and_b32_e32 v4, 0xffff0000, v47
	v_pk_mul_f32 v[4:5], v[4:5], v[4:5]
	s_nop 0
	v_add_f32_e32 v4, v4, v46
	v_add_f32_e32 v46, v5, v4
	v_lshlrev_b32_e32 v5, 16, v49
	v_and_b32_e32 v4, 0xffff0000, v48
	v_pk_mul_f32 v[4:5], v[4:5], v[4:5]
	s_nop 0
	v_add_f32_e32 v4, v4, v46
	v_add_f32_e32 v46, v5, v4
	v_and_b32_e32 v4, 0xffff0000, v49
	v_fmac_f32_e32 v46, v4, v4
	v_lshlrev_b32_e32 v4, 16, v42
	v_fmac_f32_e32 v46, v4, v4
	v_lshlrev_b32_e32 v5, 16, v43
	v_and_b32_e32 v4, 0xffff0000, v42
	v_pk_mul_f32 v[4:5], v[4:5], v[4:5]
	s_nop 0
	v_add_f32_e32 v4, v4, v46
	v_add_f32_e32 v42, v5, v4
	v_lshlrev_b32_e32 v5, 16, v44
	v_and_b32_e32 v4, 0xffff0000, v43
	v_pk_mul_f32 v[4:5], v[4:5], v[4:5]
	s_nop 0
	v_add_f32_e32 v4, v4, v42
	v_add_f32_e32 v42, v5, v4
	v_lshlrev_b32_e32 v5, 16, v45
	v_and_b32_e32 v4, 0xffff0000, v44
	v_pk_mul_f32 v[4:5], v[4:5], v[4:5]
	s_nop 0
	v_add_f32_e32 v4, v4, v42
	v_add_f32_e32 v42, v5, v4
	v_and_b32_e32 v4, 0xffff0000, v45
	v_fmac_f32_e32 v42, v4, v4
	v_lshlrev_b32_e32 v4, 16, v38
	v_fmac_f32_e32 v42, v4, v4
	v_lshlrev_b32_e32 v5, 16, v39
	v_and_b32_e32 v4, 0xffff0000, v38
	v_pk_mul_f32 v[4:5], v[4:5], v[4:5]
	s_nop 0
	v_add_f32_e32 v4, v4, v42
	v_add_f32_e32 v38, v5, v4
	v_lshlrev_b32_e32 v5, 16, v40
	v_and_b32_e32 v4, 0xffff0000, v39
	v_pk_mul_f32 v[4:5], v[4:5], v[4:5]
	s_nop 0
	v_add_f32_e32 v4, v4, v38
	v_add_f32_e32 v38, v5, v4
	v_lshlrev_b32_e32 v5, 16, v41
	v_and_b32_e32 v4, 0xffff0000, v40
	v_pk_mul_f32 v[4:5], v[4:5], v[4:5]
	s_nop 0
	v_add_f32_e32 v4, v4, v38
	v_add_f32_e32 v4, v5, v4
	v_and_b32_e32 v5, 0xffff0000, v41
	v_fmac_f32_e32 v4, v5, v5
	s_mov_b64 s[16:17], 0x100
	v_and_b32_e32 v6, 64, v200
	v_xor_b32_e32 v5, 1, v200
	v_add_u32_e32 v6, 64, v6
	v_cmp_lt_i32_e32 vcc, v5, v6
	s_mov_b32 s2, 0x800000
	s_nop 0
	v_cndmask_b32_e32 v5, v200, v5, vcc
	v_lshlrev_b32_e32 v5, 2, v5
	ds_bpermute_b32 v5, v5, v4
	s_waitcnt lgkmcnt(0)
	v_add_f32_e32 v4, v4, v5
	v_fmamk_f32 v4, v4, 0x3b800000, v198
	v_mul_f32_e32 v5, 0x4b800000, v4
	v_cmp_gt_f32_e32 vcc, s2, v4
	s_nop 1
	v_cndmask_b32_e32 v4, v4, v5, vcc
	v_rsq_f32_e32 v4, v4
	s_nop 0
	v_mul_f32_e32 v5, 0x45800000, v4
	v_cndmask_b32_e32 v4, v4, v5, vcc
	v_cmp_eq_u32_e32 vcc, 0, v0
	s_nop 0
	s_barrier
	s_and_saveexec_b64 s[16:17], vcc
	v_lshl_add_u32 v5, v54, 2, 16
	ds_write_b32 v5, v4
	s_or_b64 exec, exec, s[16:17]
	s_add_u32 s10, s10, s50
	s_addc_u32 s11, s11, s51
	s_cmp_eq_u64 s[12:13], 0
	s_cbranch_scc1 .LBB0_829
	v_mad_i64_i32 v[6:7], s[14:15], s14, v54, 0
	v_lshl_add_u64 v[6:7], v[6:7], 2, s[12:13]
	v_lshlrev_b32_e32 v8, 9, v0
	v_mov_b32_e32 v9, v1
	v_lshl_add_u64 v[6:7], v[6:7], 0, v[8:9]
	v_lshl_add_u64 v[8:9], s[10:11], 0, v[8:9]
	v_mov_b32_e32 v5, v4
	s_mov_b64 s[12:13], 0

.LBB0_1152:
	global_load_dwordx4 v[6:9], v[2:3], off offset:16
	global_load_dwordx4 v[10:13], v[2:3], off
	global_load_dwordx4 v[14:17], v[2:3], off offset:-16
	global_load_dwordx4 v[18:21], v[2:3], off offset:-32
	global_load_dwordx4 v[24:27], v[2:3], off offset:80
	global_load_dwordx4 v[28:31], v[2:3], off offset:64
	global_load_dwordx4 v[32:35], v[2:3], off offset:48
	global_load_dwordx4 v[36:39], v[2:3], off offset:32
	global_load_dwordx4 v[40:43], v[2:3], off offset:144
	global_load_dwordx4 v[44:47], v[2:3], off offset:128
	global_load_dwordx4 v[48:51], v[2:3], off offset:112
	global_load_dwordx4 v[52:55], v[2:3], off offset:96
	global_load_dwordx4 v[66:69], v[2:3], off offset:208
	global_load_dwordx4 v[70:73], v[2:3], off offset:192
	global_load_dwordx4 v[74:77], v[2:3], off offset:176
	global_load_dwordx4 v[78:81], v[2:3], off offset:160
	global_load_dwordx4 v[102:105], v[2:3], off offset:272
	global_load_dwordx4 v[106:109], v[2:3], off offset:256
	global_load_dwordx4 v[118:121], v[2:3], off offset:240
	global_load_dwordx4 v[122:125], v[2:3], off offset:224
	global_load_dwordx4 v[130:133], v[2:3], off offset:336
	global_load_dwordx4 v[134:137], v[2:3], off offset:320
	global_load_dwordx4 v[82:85], v[2:3], off offset:304
	global_load_dwordx4 v[56:59], v[2:3], off offset:288
	s_waitcnt vmcnt(20)
	v_lshlrev_b32_e32 v5, 16, v18
	v_lshlrev_b32_e32 v23, 16, v19
	v_and_b32_e32 v22, 0xffff0000, v18
	v_fmac_f32_e32 v0, v5, v5
	v_pk_mul_f32 v[22:23], v[22:23], v[22:23]
	v_and_b32_e32 v5, 0xffff0000, v21
	v_add_f32_e32 v0, v22, v0
	v_add_f32_e32 v0, v23, v0
	v_lshlrev_b32_e32 v23, 16, v20
	v_and_b32_e32 v22, 0xffff0000, v19
	v_pk_mul_f32 v[18:19], v[22:23], v[22:23]
	s_nop 0
	v_add_f32_e32 v0, v18, v0
	v_add_f32_e32 v0, v19, v0
	v_lshlrev_b32_e32 v19, 16, v21
	v_and_b32_e32 v18, 0xffff0000, v20
	v_pk_mul_f32 v[18:19], v[18:19], v[18:19]
	s_nop 0
	v_add_f32_e32 v0, v18, v0
	v_add_f32_e32 v0, v19, v0
	v_fmac_f32_e32 v0, v5, v5
	v_lshlrev_b32_e32 v5, 16, v14
	v_lshlrev_b32_e32 v19, 16, v15
	v_and_b32_e32 v18, 0xffff0000, v14
	v_fmac_f32_e32 v0, v5, v5
	v_pk_mul_f32 v[18:19], v[18:19], v[18:19]
	v_and_b32_e32 v5, 0xffff0000, v17
	v_add_f32_e32 v0, v18, v0
	v_add_f32_e32 v0, v19, v0
	v_lshlrev_b32_e32 v19, 16, v16
	v_and_b32_e32 v18, 0xffff0000, v15
	v_pk_mul_f32 v[14:15], v[18:19], v[18:19]
	s_nop 0
	v_add_f32_e32 v0, v14, v0
	v_add_f32_e32 v0, v15, v0
	v_lshlrev_b32_e32 v15, 16, v17
	v_and_b32_e32 v14, 0xffff0000, v16
	v_pk_mul_f32 v[14:15], v[14:15], v[14:15]
	s_nop 0
	v_add_f32_e32 v0, v14, v0
	v_add_f32_e32 v0, v15, v0
	v_fmac_f32_e32 v0, v5, v5
	v_lshlrev_b32_e32 v5, 16, v10
	v_lshlrev_b32_e32 v15, 16, v11
	v_and_b32_e32 v14, 0xffff0000, v10
	v_fmac_f32_e32 v0, v5, v5
	v_pk_mul_f32 v[14:15], v[14:15], v[14:15]
	v_and_b32_e32 v5, 0xffff0000, v13
	v_add_f32_e32 v0, v14, v0
	v_add_f32_e32 v0, v15, v0
	v_lshlrev_b32_e32 v15, 16, v12
	v_and_b32_e32 v14, 0xffff0000, v11
	v_pk_mul_f32 v[10:11], v[14:15], v[14:15]
	s_nop 0
	v_add_f32_e32 v0, v10, v0
	v_add_f32_e32 v0, v11, v0
	v_lshlrev_b32_e32 v11, 16, v13
	v_and_b32_e32 v10, 0xffff0000, v12
	v_pk_mul_f32 v[10:11], v[10:11], v[10:11]
	s_nop 0
	v_add_f32_e32 v0, v10, v0
	v_add_f32_e32 v0, v11, v0
	v_fmac_f32_e32 v0, v5, v5
	v_lshlrev_b32_e32 v5, 16, v6
	v_lshlrev_b32_e32 v11, 16, v7
	v_and_b32_e32 v10, 0xffff0000, v6
	v_fmac_f32_e32 v0, v5, v5
	v_pk_mul_f32 v[10:11], v[10:11], v[10:11]
	v_and_b32_e32 v5, 0xffff0000, v9
	v_add_f32_e32 v0, v10, v0
	v_add_f32_e32 v0, v11, v0
	v_lshlrev_b32_e32 v11, 16, v8
	v_and_b32_e32 v10, 0xffff0000, v7
	v_pk_mul_f32 v[6:7], v[10:11], v[10:11]
	s_nop 0
	v_add_f32_e32 v0, v6, v0
	v_add_f32_e32 v0, v7, v0
	v_lshlrev_b32_e32 v7, 16, v9
	v_and_b32_e32 v6, 0xffff0000, v8
	v_pk_mul_f32 v[6:7], v[6:7], v[6:7]
	s_nop 0
	v_add_f32_e32 v0, v6, v0
	v_add_f32_e32 v0, v7, v0
	v_fmac_f32_e32 v0, v5, v5
	s_waitcnt vmcnt(16)
	v_lshlrev_b32_e32 v5, 16, v36
	v_lshlrev_b32_e32 v23, 16, v37
	v_and_b32_e32 v22, 0xffff0000, v36
	v_fmac_f32_e32 v0, v5, v5
	v_pk_mul_f32 v[22:23], v[22:23], v[22:23]
	v_and_b32_e32 v5, 0xffff0000, v39
	v_add_f32_e32 v0, v22, v0
	v_add_f32_e32 v0, v23, v0
	v_lshlrev_b32_e32 v23, 16, v38
	v_and_b32_e32 v22, 0xffff0000, v37
	v_pk_mul_f32 v[36:37], v[22:23], v[22:23]
	s_nop 0
	v_add_f32_e32 v0, v36, v0
	v_add_f32_e32 v0, v37, v0
	v_lshlrev_b32_e32 v37, 16, v39
	v_and_b32_e32 v36, 0xffff0000, v38
	v_pk_mul_f32 v[36:37], v[36:37], v[36:37]
	s_nop 0
	v_add_f32_e32 v0, v36, v0
	v_add_f32_e32 v0, v37, v0
	v_fmac_f32_e32 v0, v5, v5
	v_lshlrev_b32_e32 v5, 16, v32
	v_lshlrev_b32_e32 v37, 16, v33
	v_and_b32_e32 v36, 0xffff0000, v32
	v_fmac_f32_e32 v0, v5, v5
	v_pk_mul_f32 v[36:37], v[36:37], v[36:37]
	v_and_b32_e32 v5, 0xffff0000, v35
	v_add_f32_e32 v0, v36, v0
	v_add_f32_e32 v0, v37, v0
	v_lshlrev_b32_e32 v37, 16, v34
	v_and_b32_e32 v36, 0xffff0000, v33
	v_pk_mul_f32 v[32:33], v[36:37], v[36:37]
	s_nop 0
	v_add_f32_e32 v0, v32, v0
	v_add_f32_e32 v0, v33, v0
	v_lshlrev_b32_e32 v33, 16, v35
	v_and_b32_e32 v32, 0xffff0000, v34
	v_pk_mul_f32 v[32:33], v[32:33], v[32:33]
	s_nop 0
	v_add_f32_e32 v0, v32, v0
	v_add_f32_e32 v0, v33, v0
	v_fmac_f32_e32 v0, v5, v5
	v_lshlrev_b32_e32 v5, 16, v28
	v_lshlrev_b32_e32 v33, 16, v29
	v_and_b32_e32 v32, 0xffff0000, v28
	v_fmac_f32_e32 v0, v5, v5
	v_pk_mul_f32 v[32:33], v[32:33], v[32:33]
	v_and_b32_e32 v5, 0xffff0000, v31
	v_add_f32_e32 v0, v32, v0
	v_add_f32_e32 v0, v33, v0
	v_lshlrev_b32_e32 v33, 16, v30
	v_and_b32_e32 v32, 0xffff0000, v29
	v_pk_mul_f32 v[28:29], v[32:33], v[32:33]
	s_nop 0
	v_add_f32_e32 v0, v28, v0
	v_add_f32_e32 v0, v29, v0
	v_lshlrev_b32_e32 v29, 16, v31
	v_and_b32_e32 v28, 0xffff0000, v30
	v_pk_mul_f32 v[28:29], v[28:29], v[28:29]
	s_nop 0
	v_add_f32_e32 v0, v28, v0
	v_add_f32_e32 v0, v29, v0
	v_fmac_f32_e32 v0, v5, v5
	v_lshlrev_b32_e32 v5, 16, v24
	v_lshlrev_b32_e32 v29, 16, v25
	v_and_b32_e32 v28, 0xffff0000, v24
	v_fmac_f32_e32 v0, v5, v5
	v_pk_mul_f32 v[28:29], v[28:29], v[28:29]
	v_and_b32_e32 v5, 0xffff0000, v27
	v_add_f32_e32 v0, v28, v0
	v_add_f32_e32 v0, v29, v0
	v_lshlrev_b32_e32 v29, 16, v26
	v_and_b32_e32 v28, 0xffff0000, v25
	v_pk_mul_f32 v[24:25], v[28:29], v[28:29]
	s_nop 0
	v_add_f32_e32 v0, v24, v0
	v_add_f32_e32 v0, v25, v0
	v_lshlrev_b32_e32 v25, 16, v27
	v_and_b32_e32 v24, 0xffff0000, v26
	v_pk_mul_f32 v[24:25], v[24:25], v[24:25]
	s_nop 0
	v_add_f32_e32 v0, v24, v0
	v_add_f32_e32 v0, v25, v0
	v_fmac_f32_e32 v0, v5, v5
	s_waitcnt vmcnt(12)
	v_lshlrev_b32_e32 v5, 16, v52
	v_lshlrev_b32_e32 v23, 16, v53
	v_and_b32_e32 v22, 0xffff0000, v52
	v_fmac_f32_e32 v0, v5, v5
	v_pk_mul_f32 v[22:23], v[22:23], v[22:23]
	v_and_b32_e32 v5, 0xffff0000, v55
	v_add_f32_e32 v0, v22, v0
	v_add_f32_e32 v0, v23, v0
	v_lshlrev_b32_e32 v23, 16, v54
	v_and_b32_e32 v22, 0xffff0000, v53
	v_pk_mul_f32 v[52:53], v[22:23], v[22:23]
	s_nop 0
	v_add_f32_e32 v0, v52, v0
	v_add_f32_e32 v0, v53, v0
	v_lshlrev_b32_e32 v53, 16, v55
	v_and_b32_e32 v52, 0xffff0000, v54
	v_pk_mul_f32 v[52:53], v[52:53], v[52:53]
	s_nop 0
	v_add_f32_e32 v0, v52, v0
	v_add_f32_e32 v0, v53, v0
	v_fmac_f32_e32 v0, v5, v5
	v_lshlrev_b32_e32 v5, 16, v48
	v_lshlrev_b32_e32 v53, 16, v49
	v_and_b32_e32 v52, 0xffff0000, v48
	v_fmac_f32_e32 v0, v5, v5
	v_pk_mul_f32 v[52:53], v[52:53], v[52:53]
	v_and_b32_e32 v5, 0xffff0000, v51
	v_add_f32_e32 v0, v52, v0
	v_add_f32_e32 v0, v53, v0
	v_lshlrev_b32_e32 v53, 16, v50
	v_and_b32_e32 v52, 0xffff0000, v49
	v_pk_mul_f32 v[48:49], v[52:53], v[52:53]
	s_nop 0
	v_add_f32_e32 v0, v48, v0
	v_add_f32_e32 v0, v49, v0
	v_lshlrev_b32_e32 v49, 16, v51
	v_and_b32_e32 v48, 0xffff0000, v50
	v_pk_mul_f32 v[48:49], v[48:49], v[48:49]
	s_nop 0
	v_add_f32_e32 v0, v48, v0
	v_add_f32_e32 v0, v49, v0
	v_fmac_f32_e32 v0, v5, v5
	v_lshlrev_b32_e32 v5, 16, v44
	v_lshlrev_b32_e32 v49, 16, v45
	v_and_b32_e32 v48, 0xffff0000, v44
	v_fmac_f32_e32 v0, v5, v5
	v_pk_mul_f32 v[48:49], v[48:49], v[48:49]
	v_and_b32_e32 v5, 0xffff0000, v47
	v_add_f32_e32 v0, v48, v0
	v_add_f32_e32 v0, v49, v0
	v_lshlrev_b32_e32 v49, 16, v46
	v_and_b32_e32 v48, 0xffff0000, v45
	v_pk_mul_f32 v[44:45], v[48:49], v[48:49]
	s_nop 0
	v_add_f32_e32 v0, v44, v0
	v_add_f32_e32 v0, v45, v0
	v_lshlrev_b32_e32 v45, 16, v47
	v_and_b32_e32 v44, 0xffff0000, v46
	v_pk_mul_f32 v[44:45], v[44:45], v[44:45]
	s_nop 0
	v_add_f32_e32 v0, v44, v0
	v_add_f32_e32 v0, v45, v0
	v_fmac_f32_e32 v0, v5, v5
	v_lshlrev_b32_e32 v5, 16, v40
	v_lshlrev_b32_e32 v45, 16, v41
	v_and_b32_e32 v44, 0xffff0000, v40
	v_fmac_f32_e32 v0, v5, v5
	v_pk_mul_f32 v[44:45], v[44:45], v[44:45]
	v_and_b32_e32 v5, 0xffff0000, v43
	v_add_f32_e32 v0, v44, v0
	v_add_f32_e32 v0, v45, v0
	v_lshlrev_b32_e32 v45, 16, v42
	v_and_b32_e32 v44, 0xffff0000, v41
	v_pk_mul_f32 v[40:41], v[44:45], v[44:45]
	s_nop 0
	v_add_f32_e32 v0, v40, v0
	v_add_f32_e32 v0, v41, v0
	v_lshlrev_b32_e32 v41, 16, v43
	v_and_b32_e32 v40, 0xffff0000, v42
	v_pk_mul_f32 v[40:41], v[40:41], v[40:41]
	s_nop 0
	v_add_f32_e32 v0, v40, v0
	v_add_f32_e32 v0, v41, v0
	v_fmac_f32_e32 v0, v5, v5
	s_waitcnt vmcnt(8)
	v_lshlrev_b32_e32 v5, 16, v78
	v_lshlrev_b32_e32 v23, 16, v79
	v_and_b32_e32 v22, 0xffff0000, v78
	v_fmac_f32_e32 v0, v5, v5
	v_pk_mul_f32 v[22:23], v[22:23], v[22:23]
	v_and_b32_e32 v5, 0xffff0000, v81
	v_add_f32_e32 v0, v22, v0
	v_add_f32_e32 v0, v23, v0
	v_lshlrev_b32_e32 v23, 16, v80
	v_and_b32_e32 v22, 0xffff0000, v79
	v_pk_mul_f32 v[78:79], v[22:23], v[22:23]
	s_nop 0
	v_add_f32_e32 v0, v78, v0
	v_add_f32_e32 v0, v79, v0
	v_lshlrev_b32_e32 v79, 16, v81
	v_and_b32_e32 v78, 0xffff0000, v80
	v_pk_mul_f32 v[78:79], v[78:79], v[78:79]
	s_nop 0
	v_add_f32_e32 v0, v78, v0
	v_add_f32_e32 v0, v79, v0
	v_fmac_f32_e32 v0, v5, v5
	v_lshlrev_b32_e32 v5, 16, v74
	v_lshlrev_b32_e32 v79, 16, v75
	v_and_b32_e32 v78, 0xffff0000, v74
	v_fmac_f32_e32 v0, v5, v5
	v_pk_mul_f32 v[78:79], v[78:79], v[78:79]
	v_and_b32_e32 v5, 0xffff0000, v77
	v_add_f32_e32 v0, v78, v0
	v_add_f32_e32 v0, v79, v0
	v_lshlrev_b32_e32 v79, 16, v76
	v_and_b32_e32 v78, 0xffff0000, v75
	v_pk_mul_f32 v[74:75], v[78:79], v[78:79]
	s_nop 0
	v_add_f32_e32 v0, v74, v0
	v_add_f32_e32 v0, v75, v0
	v_lshlrev_b32_e32 v75, 16, v77
	v_and_b32_e32 v74, 0xffff0000, v76
	v_pk_mul_f32 v[74:75], v[74:75], v[74:75]
	s_nop 0
	v_add_f32_e32 v0, v74, v0
	v_add_f32_e32 v0, v75, v0
	v_fmac_f32_e32 v0, v5, v5
	v_lshlrev_b32_e32 v5, 16, v70
	v_lshlrev_b32_e32 v75, 16, v71
	v_and_b32_e32 v74, 0xffff0000, v70
	v_fmac_f32_e32 v0, v5, v5
	v_pk_mul_f32 v[74:75], v[74:75], v[74:75]
	v_and_b32_e32 v5, 0xffff0000, v73
	v_add_f32_e32 v0, v74, v0
	v_add_f32_e32 v0, v75, v0
	v_lshlrev_b32_e32 v75, 16, v72
	v_and_b32_e32 v74, 0xffff0000, v71
	v_pk_mul_f32 v[70:71], v[74:75], v[74:75]
	s_nop 0
	v_add_f32_e32 v0, v70, v0
	v_add_f32_e32 v0, v71, v0
	v_lshlrev_b32_e32 v71, 16, v73
	v_and_b32_e32 v70, 0xffff0000, v72
	v_pk_mul_f32 v[70:71], v[70:71], v[70:71]
	s_nop 0
	v_add_f32_e32 v0, v70, v0
	v_add_f32_e32 v0, v71, v0
	v_fmac_f32_e32 v0, v5, v5
	v_lshlrev_b32_e32 v5, 16, v66
	v_lshlrev_b32_e32 v71, 16, v67
	v_and_b32_e32 v70, 0xffff0000, v66
	v_fmac_f32_e32 v0, v5, v5
	v_pk_mul_f32 v[70:71], v[70:71], v[70:71]
	v_and_b32_e32 v5, 0xffff0000, v69
	v_add_f32_e32 v0, v70, v0
	v_add_f32_e32 v0, v71, v0
	v_lshlrev_b32_e32 v71, 16, v68
	v_and_b32_e32 v70, 0xffff0000, v67
	v_pk_mul_f32 v[66:67], v[70:71], v[70:71]
	s_nop 0
	v_add_f32_e32 v0, v66, v0
	v_add_f32_e32 v0, v67, v0
	v_lshlrev_b32_e32 v67, 16, v69
	v_and_b32_e32 v66, 0xffff0000, v68
	v_pk_mul_f32 v[66:67], v[66:67], v[66:67]
	s_nop 0
	v_add_f32_e32 v0, v66, v0
	v_add_f32_e32 v0, v67, v0
	v_fmac_f32_e32 v0, v5, v5
	s_waitcnt vmcnt(4)
	v_lshlrev_b32_e32 v5, 16, v122
	v_lshlrev_b32_e32 v23, 16, v123
	v_and_b32_e32 v22, 0xffff0000, v122
	v_fmac_f32_e32 v0, v5, v5
	v_pk_mul_f32 v[22:23], v[22:23], v[22:23]
	v_and_b32_e32 v5, 0xffff0000, v125
	v_add_f32_e32 v0, v22, v0
	v_add_f32_e32 v0, v23, v0
	v_lshlrev_b32_e32 v23, 16, v124
	v_and_b32_e32 v22, 0xffff0000, v123
	v_pk_mul_f32 v[122:123], v[22:23], v[22:23]
	s_nop 0
	v_add_f32_e32 v0, v122, v0
	v_add_f32_e32 v0, v123, v0
	v_lshlrev_b32_e32 v123, 16, v125
	v_and_b32_e32 v122, 0xffff0000, v124
	v_pk_mul_f32 v[122:123], v[122:123], v[122:123]
	s_nop 0
	v_add_f32_e32 v0, v122, v0
	v_add_f32_e32 v0, v123, v0
	v_fmac_f32_e32 v0, v5, v5
	v_lshlrev_b32_e32 v5, 16, v118
	v_lshlrev_b32_e32 v123, 16, v119
	v_and_b32_e32 v122, 0xffff0000, v118
	v_fmac_f32_e32 v0, v5, v5
	v_pk_mul_f32 v[122:123], v[122:123], v[122:123]
	v_and_b32_e32 v5, 0xffff0000, v121
	v_add_f32_e32 v0, v122, v0
	v_add_f32_e32 v0, v123, v0
	v_lshlrev_b32_e32 v123, 16, v120
	v_and_b32_e32 v122, 0xffff0000, v119
	v_pk_mul_f32 v[118:119], v[122:123], v[122:123]
	s_nop 0
	v_add_f32_e32 v0, v118, v0
	v_add_f32_e32 v0, v119, v0
	v_lshlrev_b32_e32 v119, 16, v121
	v_and_b32_e32 v118, 0xffff0000, v120
	v_pk_mul_f32 v[118:119], v[118:119], v[118:119]
	s_nop 0
	v_add_f32_e32 v0, v118, v0
	v_add_f32_e32 v0, v119, v0
	v_fmac_f32_e32 v0, v5, v5
	v_lshlrev_b32_e32 v5, 16, v106
	v_lshlrev_b32_e32 v119, 16, v107
	v_and_b32_e32 v118, 0xffff0000, v106
	v_fmac_f32_e32 v0, v5, v5
	v_pk_mul_f32 v[118:119], v[118:119], v[118:119]
	v_and_b32_e32 v5, 0xffff0000, v109
	v_add_f32_e32 v0, v118, v0
	v_add_f32_e32 v0, v119, v0
	v_lshlrev_b32_e32 v119, 16, v108
	v_and_b32_e32 v118, 0xffff0000, v107
	v_pk_mul_f32 v[106:107], v[118:119], v[118:119]
	s_nop 0
	v_add_f32_e32 v0, v106, v0
	v_add_f32_e32 v0, v107, v0
	v_lshlrev_b32_e32 v107, 16, v109
	v_and_b32_e32 v106, 0xffff0000, v108
	v_pk_mul_f32 v[106:107], v[106:107], v[106:107]
	s_nop 0
	v_add_f32_e32 v0, v106, v0
	v_add_f32_e32 v0, v107, v0
	v_fmac_f32_e32 v0, v5, v5
	v_lshlrev_b32_e32 v5, 16, v102
	v_lshlrev_b32_e32 v107, 16, v103
	v_and_b32_e32 v106, 0xffff0000, v102
	v_fmac_f32_e32 v0, v5, v5
	v_pk_mul_f32 v[106:107], v[106:107], v[106:107]
	v_and_b32_e32 v5, 0xffff0000, v105
	v_add_f32_e32 v0, v106, v0
	v_add_f32_e32 v0, v107, v0
	v_lshlrev_b32_e32 v107, 16, v104
	v_and_b32_e32 v106, 0xffff0000, v103
	v_pk_mul_f32 v[102:103], v[106:107], v[106:107]
	s_nop 0
	v_add_f32_e32 v0, v102, v0
	v_add_f32_e32 v0, v103, v0
	v_lshlrev_b32_e32 v103, 16, v105
	v_and_b32_e32 v102, 0xffff0000, v104
	v_pk_mul_f32 v[102:103], v[102:103], v[102:103]
	s_nop 0
	v_add_f32_e32 v0, v102, v0
	v_add_f32_e32 v0, v103, v0
	v_fmac_f32_e32 v0, v5, v5
	s_waitcnt vmcnt(0)
	v_lshlrev_b32_e32 v5, 16, v56
	v_lshlrev_b32_e32 v23, 16, v57
	v_and_b32_e32 v22, 0xffff0000, v56
	v_fmac_f32_e32 v0, v5, v5
	v_pk_mul_f32 v[22:23], v[22:23], v[22:23]
	v_and_b32_e32 v5, 0xffff0000, v59
	v_add_f32_e32 v0, v22, v0
	v_add_f32_e32 v0, v23, v0
	v_lshlrev_b32_e32 v23, 16, v58
	v_and_b32_e32 v22, 0xffff0000, v57
	v_pk_mul_f32 v[56:57], v[22:23], v[22:23]
	s_nop 0
	v_add_f32_e32 v0, v56, v0
	v_add_f32_e32 v0, v57, v0
	v_lshlrev_b32_e32 v57, 16, v59
	v_and_b32_e32 v56, 0xffff0000, v58
	v_pk_mul_f32 v[56:57], v[56:57], v[56:57]
	s_nop 0
	v_add_f32_e32 v0, v56, v0
	v_add_f32_e32 v0, v57, v0
	v_fmac_f32_e32 v0, v5, v5
	v_lshlrev_b32_e32 v5, 16, v82
	v_lshlrev_b32_e32 v57, 16, v83
	v_and_b32_e32 v56, 0xffff0000, v82
	v_fmac_f32_e32 v0, v5, v5
	v_pk_mul_f32 v[56:57], v[56:57], v[56:57]
	v_and_b32_e32 v5, 0xffff0000, v85
	v_add_f32_e32 v0, v56, v0
	v_add_f32_e32 v0, v57, v0
	v_lshlrev_b32_e32 v57, 16, v84
	v_and_b32_e32 v56, 0xffff0000, v83
	v_pk_mul_f32 v[82:83], v[56:57], v[56:57]
	s_nop 0
	v_add_f32_e32 v0, v82, v0
	v_add_f32_e32 v0, v83, v0
	v_lshlrev_b32_e32 v83, 16, v85
	v_and_b32_e32 v82, 0xffff0000, v84
	v_pk_mul_f32 v[82:83], v[82:83], v[82:83]
	s_nop 0
	v_add_f32_e32 v0, v82, v0
	v_add_f32_e32 v0, v83, v0
	v_fmac_f32_e32 v0, v5, v5
	v_lshlrev_b32_e32 v5, 16, v134
	v_lshlrev_b32_e32 v83, 16, v135
	v_and_b32_e32 v82, 0xffff0000, v134
	v_fmac_f32_e32 v0, v5, v5
	v_pk_mul_f32 v[82:83], v[82:83], v[82:83]
	v_and_b32_e32 v5, 0xffff0000, v137
	v_add_f32_e32 v0, v82, v0
	v_add_f32_e32 v0, v83, v0
	v_lshlrev_b32_e32 v83, 16, v136
	v_and_b32_e32 v82, 0xffff0000, v135
	v_pk_mul_f32 v[134:135], v[82:83], v[82:83]
	s_nop 0
	v_add_f32_e32 v0, v134, v0
	v_add_f32_e32 v0, v135, v0
	v_lshlrev_b32_e32 v135, 16, v137
	v_and_b32_e32 v134, 0xffff0000, v136
	v_pk_mul_f32 v[134:135], v[134:135], v[134:135]
	s_nop 0
	v_add_f32_e32 v0, v134, v0
	v_add_f32_e32 v0, v135, v0
	v_fmac_f32_e32 v0, v5, v5
	v_lshlrev_b32_e32 v5, 16, v130
	v_lshlrev_b32_e32 v135, 16, v131
	v_and_b32_e32 v134, 0xffff0000, v130
	v_fmac_f32_e32 v0, v5, v5
	v_pk_mul_f32 v[134:135], v[134:135], v[134:135]
	v_and_b32_e32 v5, 0xffff0000, v133
	v_add_f32_e32 v0, v134, v0
	v_add_f32_e32 v0, v135, v0
	v_lshlrev_b32_e32 v135, 16, v132
	v_and_b32_e32 v134, 0xffff0000, v131
	v_pk_mul_f32 v[130:131], v[134:135], v[134:135]
	s_nop 0
	v_add_f32_e32 v0, v130, v0
	v_add_f32_e32 v0, v131, v0
	v_lshlrev_b32_e32 v131, 16, v133
	v_and_b32_e32 v130, 0xffff0000, v132
	v_pk_mul_f32 v[130:131], v[130:131], v[130:131]
	s_nop 0
	v_add_f32_e32 v0, v130, v0
	v_add_f32_e32 v0, v131, v0
	v_fmac_f32_e32 v0, v5, v5
	s_mov_b64 s[10:11], 0x180
	v_and_b32_e32 v3, 64, v200
	v_xor_b32_e32 v2, 1, v200
	v_add_u32_e32 v171, 64, v3
	v_cmp_lt_i32_e32 vcc, v2, v171
	s_mov_b32 s2, 0x43c00000
	s_nop 0
	v_cndmask_b32_e32 v2, v200, v2, vcc
	v_lshlrev_b32_e32 v2, 2, v2
	ds_bpermute_b32 v2, v2, v0
	s_waitcnt lgkmcnt(0)
	v_add_f32_e32 v0, v0, v2
	v_div_scale_f32 v2, s[10:11], s2, s2, v0
	v_rcp_f32_e32 v3, v2
	v_div_scale_f32 v5, vcc, v0, s2, v0
	v_fma_f32 v6, -v2, v3, 1.0
	v_fmac_f32_e32 v3, v6, v3
	v_mul_f32_e32 v6, v5, v3
	v_fma_f32 v7, -v2, v6, v5
	v_fmac_f32_e32 v6, v7, v3
	v_fma_f32 v2, -v2, v6, v5
	v_div_fmas_f32 v2, v2, v3, v6
	v_div_fixup_f32 v0, v2, s2, v0
	v_add_f32_e32 v0, 0x358637bd, v0
	s_mov_b32 s2, 0x800000
	v_mul_f32_e32 v2, 0x4b800000, v0
	v_cmp_gt_f32_e32 vcc, s2, v0
	s_nop 1
	v_cndmask_b32_e32 v0, v0, v2, vcc
	v_rsq_f32_e32 v0, v0
	s_nop 0
	v_mul_f32_e32 v2, 0x45800000, v0
	v_cndmask_b32_e32 v0, v0, v2, vcc
	v_cmp_eq_u32_e32 vcc, 0, v4
	s_nop 0
	s_barrier
	s_and_saveexec_b64 s[10:11], vcc
	s_mov_b32 s13, 0xfffffc0
	v_lshl_add_u32 v2, v63, 2, 16
	ds_write_b32 v2, v0
	s_or_b64 exec, exec, s[10:11]
	v_ashrrev_i32_e32 v65, 3, v62
	v_lshl_add_u32 v0, v65, 2, 16
	s_lshr_b32 s2, s8, 2
	s_waitcnt lgkmcnt(0)
	s_barrier
	ds_read2_b32 v[174:175], v0 offset1:32
	ds_read2_b32 v[172:173], v0 offset0:64 offset1:96
	v_lshlrev_b32_e32 v0, 3, v62
	v_and_b32_e32 v4, 56, v0
	v_lshl_add_u32 v0, s2, 7, v65
	v_mov_b64_e32 v[2:3], s[50:51]
	s_movk_i32 s6, 0x300
	v_mad_i64_i32 v[2:3], s[10:11], v0, s6, v[2:3]
	v_lshlrev_b32_e32 v0, 1, v4
	v_lshl_add_u64 v[178:179], v[2:3], 0, v[0:1]
	v_add_u32_e32 v5, s12, v65
	v_mov_b64_e32 v[2:3], s[46:47]
	v_mad_i64_i32 v[2:3], s[10:11], v5, s6, v[2:3]
	v_lshl_add_u64 v[186:187], v[2:3], 0, v[0:1]
	s_movk_i32 s6, 0x6000
	v_add_co_u32_e32 v188, vcc, s6, v186
	s_mov_b32 s10, 0xc000
	s_nop 0
	v_addc_co_u32_e32 v189, vcc, 0, v187, vcc
	v_add_co_u32_e32 v190, vcc, s10, v186
	s_waitcnt lgkmcnt(0)
	s_barrier
	global_load_dwordx4 v[66:69], v[186:187], off
	global_load_dwordx4 v[50:53], v[188:189], off
	v_addc_co_u32_e32 v191, vcc, 0, v187, vcc
	v_add_co_u32_e32 v192, vcc, s30, v186
	v_lshlrev_b32_e32 v211, 2, v4
	s_nop 0
	v_addc_co_u32_e32 v193, vcc, 0, v187, vcc
	global_load_dwordx4 v[46:49], v[190:191], off
	global_load_dwordx4 v[42:45], v[192:193], off
	global_load_dwordx4 v[54:57], v211, s[48:49] offset:16
	global_load_dwordx4 v[70:73], v211, s[48:49]
	global_load_dwordx4 v[58:61], v[178:179], off
	v_add_co_u32_e32 v180, vcc, s6, v178
	v_mul_lo_u32 v65, v65, s34
	s_nop 0
	v_addc_co_u32_e32 v181, vcc, 0, v179, vcc
	v_add_co_u32_e32 v182, vcc, s10, v178
	global_load_dwordx4 v[74:77], v[180:181], off
	s_nop 0
	v_addc_co_u32_e32 v183, vcc, 0, v179, vcc
	global_load_dwordx4 v[78:81], v[182:183], off
	v_add_co_u32_e32 v184, vcc, s30, v178
	v_add3_u32 v177, 16, v65, v0
	s_nop 0
	v_addc_co_u32_e32 v185, vcc, 0, v179, vcc
	global_load_dwordx4 v[82:85], v[184:185], off
	global_load_dwordx4 v[14:17], v[186:187], off offset:128
	global_load_dwordx4 v[10:13], v[188:189], off offset:128
	global_load_dwordx4 v[6:9], v[190:191], off offset:128
	global_load_dwordx4 v[2:5], v[192:193], off offset:128
	global_load_dwordx4 v[34:37], v211, s[48:49] offset:272
	global_load_dwordx4 v[38:41], v211, s[48:49] offset:256
	global_load_dwordx4 v[18:21], v[178:179], off offset:128
	global_load_dwordx4 v[22:25], v[180:181], off offset:128
	global_load_dwordx4 v[26:29], v[182:183], off offset:128
	global_load_dwordx4 v[30:33], v[184:185], off offset:128
	global_load_dwordx4 v[134:137], v[186:187], off offset:256
	global_load_dwordx4 v[122:125], v[188:189], off offset:256
	global_load_dwordx4 v[106:109], v[190:191], off offset:256
	global_load_dwordx4 v[102:105], v[192:193], off offset:256
	global_load_dwordx4 v[118:121], v211, s[48:49] offset:528
	global_load_dwordx4 v[130:133], v211, s[48:49] offset:512
	v_mov_b32_e32 v176, v175
	v_mov_b32_e32 v0, v173
	v_and_b32_e32 v64, 31, v62
	s_waitcnt vmcnt(25)
	v_lshlrev_b32_e32 v86, 16, v66
	v_and_b32_e32 v87, 0xffff0000, v66
	v_pk_mul_f32 v[86:87], v[174:175], v[86:87] op_sel_hi:[0,1]
	s_waitcnt vmcnt(20)
	v_pk_mul_f32 v[86:87], v[86:87], v[70:71]
	s_nop 0
	v_cvt_pk_bf16_f32 v66, v86, v87
	v_lshlrev_b32_e32 v86, 16, v67
	v_and_b32_e32 v87, 0xffff0000, v67
	v_pk_mul_f32 v[86:87], v[174:175], v[86:87] op_sel_hi:[0,1]
	v_pk_mul_f32 v[86:87], v[86:87], v[72:73]
	s_nop 0
	v_cvt_pk_bf16_f32 v67, v86, v87
	v_lshlrev_b32_e32 v86, 16, v68
	v_and_b32_e32 v87, 0xffff0000, v68
	v_pk_mul_f32 v[86:87], v[174:175], v[86:87] op_sel_hi:[0,1]
	v_pk_mul_f32 v[86:87], v[86:87], v[54:55]
	s_nop 0
	v_cvt_pk_bf16_f32 v68, v86, v87
	v_lshlrev_b32_e32 v86, 16, v69
	v_and_b32_e32 v87, 0xffff0000, v69
	v_pk_mul_f32 v[86:87], v[174:175], v[86:87] op_sel_hi:[0,1]
	v_pk_mul_f32 v[86:87], v[86:87], v[56:57]
	s_nop 0
	v_cvt_pk_bf16_f32 v69, v86, v87
	ds_write_b128 v177, v[66:69]
	v_lshlrev_b32_e32 v66, 16, v50
	v_and_b32_e32 v67, 0xffff0000, v50
	v_pk_mul_f32 v[66:67], v[176:177], v[66:67] op_sel_hi:[0,1]
	v_pk_mul_f32 v[66:67], v[70:71], v[66:67]
	s_nop 0
	v_cvt_pk_bf16_f32 v50, v66, v67
	v_lshlrev_b32_e32 v66, 16, v51
	v_and_b32_e32 v67, 0xffff0000, v51
	v_pk_mul_f32 v[66:67], v[176:177], v[66:67] op_sel_hi:[0,1]
	v_pk_mul_f32 v[66:67], v[72:73], v[66:67]
	s_nop 0
	v_cvt_pk_bf16_f32 v51, v66, v67
	v_lshlrev_b32_e32 v66, 16, v52
	v_and_b32_e32 v67, 0xffff0000, v52
	v_pk_mul_f32 v[66:67], v[176:177], v[66:67] op_sel_hi:[0,1]
	v_pk_mul_f32 v[66:67], v[66:67], v[54:55]
	s_nop 0
	v_cvt_pk_bf16_f32 v52, v66, v67
	v_lshlrev_b32_e32 v66, 16, v53
	v_and_b32_e32 v67, 0xffff0000, v53
	v_pk_mul_f32 v[66:67], v[176:177], v[66:67] op_sel_hi:[0,1]
	v_pk_mul_f32 v[66:67], v[66:67], v[56:57]
	s_nop 0
	v_cvt_pk_bf16_f32 v53, v66, v67
	ds_write_b128 v177, v[50:53] offset:4608
	v_lshlrev_b32_e32 v50, 16, v46
	v_and_b32_e32 v51, 0xffff0000, v46
	v_pk_mul_f32 v[50:51], v[172:173], v[50:51] op_sel_hi:[0,1]
	v_pk_mul_f32 v[50:51], v[70:71], v[50:51]
	s_nop 0
	v_cvt_pk_bf16_f32 v46, v50, v51
	v_lshlrev_b32_e32 v50, 16, v47
	v_and_b32_e32 v51, 0xffff0000, v47
	v_pk_mul_f32 v[50:51], v[172:173], v[50:51] op_sel_hi:[0,1]
	v_pk_mul_f32 v[50:51], v[72:73], v[50:51]
	s_nop 0
	v_cvt_pk_bf16_f32 v47, v50, v51
	v_lshlrev_b32_e32 v50, 16, v48
	v_and_b32_e32 v51, 0xffff0000, v48
	v_pk_mul_f32 v[50:51], v[172:173], v[50:51] op_sel_hi:[0,1]
	v_pk_mul_f32 v[50:51], v[54:55], v[50:51]
	s_nop 0
	v_cvt_pk_bf16_f32 v48, v50, v51
	v_lshlrev_b32_e32 v50, 16, v49
	v_and_b32_e32 v51, 0xffff0000, v49
	v_pk_mul_f32 v[50:51], v[172:173], v[50:51] op_sel_hi:[0,1]
	v_pk_mul_f32 v[50:51], v[56:57], v[50:51]
	s_nop 0
	v_cvt_pk_bf16_f32 v49, v50, v51
	ds_write_b128 v177, v[46:49] offset:9216
	v_lshlrev_b32_e32 v46, 16, v42
	v_and_b32_e32 v47, 0xffff0000, v42
	v_pk_mul_f32 v[46:47], v[0:1], v[46:47] op_sel_hi:[0,1]
	v_pk_mul_f32 v[46:47], v[70:71], v[46:47]
	s_nop 0
	v_cvt_pk_bf16_f32 v42, v46, v47
	v_lshlrev_b32_e32 v46, 16, v43
	v_and_b32_e32 v47, 0xffff0000, v43
	v_pk_mul_f32 v[46:47], v[0:1], v[46:47] op_sel_hi:[0,1]
	v_pk_mul_f32 v[46:47], v[72:73], v[46:47]
	s_nop 0
	v_cvt_pk_bf16_f32 v43, v46, v47
	v_lshlrev_b32_e32 v46, 16, v44
	v_and_b32_e32 v47, 0xffff0000, v44
	v_pk_mul_f32 v[46:47], v[0:1], v[46:47] op_sel_hi:[0,1]
	v_pk_mul_f32 v[46:47], v[54:55], v[46:47]
	s_nop 0
	v_cvt_pk_bf16_f32 v44, v46, v47
	v_lshlrev_b32_e32 v46, 16, v45
	v_and_b32_e32 v47, 0xffff0000, v45
	v_pk_mul_f32 v[46:47], v[0:1], v[46:47] op_sel_hi:[0,1]
	v_pk_mul_f32 v[46:47], v[56:57], v[46:47]
	s_nop 0
	v_cvt_pk_bf16_f32 v45, v46, v47
	ds_write_b128 v177, v[42:45] offset:13824
	s_waitcnt vmcnt(19)
	ds_write_b128 v177, v[58:61] offset:18432
	s_waitcnt vmcnt(18)
	ds_write_b128 v177, v[74:77] offset:23040
	s_waitcnt vmcnt(17)
	ds_write_b128 v177, v[78:81] offset:27648
	s_waitcnt vmcnt(16)
	ds_write_b128 v177, v[82:85] offset:32256
	s_waitcnt vmcnt(15)
	v_lshlrev_b32_e32 v44, 16, v14
	v_and_b32_e32 v45, 0xffff0000, v14
	v_pk_mul_f32 v[44:45], v[174:175], v[44:45] op_sel_hi:[0,1]
	s_waitcnt vmcnt(10)
	v_pk_mul_f32 v[44:45], v[44:45], v[38:39]
	global_load_dwordx4 v[142:145], v[178:179], off offset:256
	global_load_dwordx4 v[146:149], v[180:181], off offset:256
	global_load_dwordx4 v[150:153], v[182:183], off offset:256
	global_load_dwordx4 v[154:157], v[184:185], off offset:256
	global_load_dwordx4 v[90:93], v[186:187], off offset:384
	global_load_dwordx4 v[94:97], v[188:189], off offset:384
	global_load_dwordx4 v[98:101], v[190:191], off offset:384
	global_load_dwordx4 v[114:117], v[192:193], off offset:384
	global_load_dwordx4 v[110:113], v211, s[48:49] offset:784
	global_load_dwordx4 v[126:129], v211, s[48:49] offset:768
	v_cvt_pk_bf16_f32 v14, v44, v45
	v_lshlrev_b32_e32 v44, 16, v15
	v_and_b32_e32 v45, 0xffff0000, v15
	v_pk_mul_f32 v[44:45], v[174:175], v[44:45] op_sel_hi:[0,1]
	v_pk_mul_f32 v[44:45], v[44:45], v[40:41]
	s_waitcnt lgkmcnt(0)
	v_cvt_pk_bf16_f32 v15, v44, v45
	v_lshlrev_b32_e32 v44, 16, v16
	v_and_b32_e32 v45, 0xffff0000, v16
	v_pk_mul_f32 v[44:45], v[174:175], v[44:45] op_sel_hi:[0,1]
	v_pk_mul_f32 v[44:45], v[44:45], v[34:35]
	s_barrier
	v_cvt_pk_bf16_f32 v16, v44, v45
	v_lshlrev_b32_e32 v44, 16, v17
	v_and_b32_e32 v45, 0xffff0000, v17
	v_pk_mul_f32 v[44:45], v[174:175], v[44:45] op_sel_hi:[0,1]
	v_pk_mul_f32 v[44:45], v[44:45], v[36:37]
	s_nop 0
	v_cvt_pk_bf16_f32 v17, v44, v45
	ds_write_b128 v177, v[14:17] offset:36864
	v_lshlrev_b32_e32 v14, 16, v10
	v_and_b32_e32 v15, 0xffff0000, v10
	v_pk_mul_f32 v[14:15], v[176:177], v[14:15] op_sel_hi:[0,1]
	v_pk_mul_f32 v[14:15], v[38:39], v[14:15]
	v_and_b32_e32 v42, 0x5f, v62
	v_cvt_pk_bf16_f32 v10, v14, v15
	v_lshlrev_b32_e32 v14, 16, v11
	v_and_b32_e32 v15, 0xffff0000, v11
	v_pk_mul_f32 v[14:15], v[176:177], v[14:15] op_sel_hi:[0,1]
	v_pk_mul_f32 v[14:15], v[40:41], v[14:15]
	v_and_or_b32 v43, v63, s13, v64
	v_cvt_pk_bf16_f32 v11, v14, v15
	v_lshlrev_b32_e32 v14, 16, v12
	v_and_b32_e32 v15, 0xffff0000, v12
	v_pk_mul_f32 v[14:15], v[176:177], v[14:15] op_sel_hi:[0,1]
	v_pk_mul_f32 v[14:15], v[14:15], v[34:35]
	v_mul_u32_u24_e32 v42, 0x48, v42
	v_cvt_pk_bf16_f32 v12, v14, v15
	v_lshlrev_b32_e32 v14, 16, v13
	v_and_b32_e32 v15, 0xffff0000, v13
	v_pk_mul_f32 v[14:15], v[176:177], v[14:15] op_sel_hi:[0,1]
	v_pk_mul_f32 v[14:15], v[14:15], v[36:37]
	s_nop 0
	v_cvt_pk_bf16_f32 v13, v14, v15
	ds_write_b128 v177, v[10:13] offset:41472
	v_lshlrev_b32_e32 v10, 16, v6
	v_and_b32_e32 v11, 0xffff0000, v6
	v_pk_mul_f32 v[10:11], v[172:173], v[10:11] op_sel_hi:[0,1]
	v_pk_mul_f32 v[10:11], v[38:39], v[10:11]
	s_nop 0
	v_cvt_pk_bf16_f32 v6, v10, v11
	v_lshlrev_b32_e32 v10, 16, v7
	v_and_b32_e32 v11, 0xffff0000, v7
	v_pk_mul_f32 v[10:11], v[172:173], v[10:11] op_sel_hi:[0,1]
	v_pk_mul_f32 v[10:11], v[40:41], v[10:11]
	s_nop 0
	v_cvt_pk_bf16_f32 v7, v10, v11
	v_lshlrev_b32_e32 v10, 16, v8
	v_and_b32_e32 v11, 0xffff0000, v8
	v_pk_mul_f32 v[10:11], v[172:173], v[10:11] op_sel_hi:[0,1]
	v_pk_mul_f32 v[10:11], v[34:35], v[10:11]
	s_nop 0
	v_cvt_pk_bf16_f32 v8, v10, v11
	v_lshlrev_b32_e32 v10, 16, v9
	v_and_b32_e32 v11, 0xffff0000, v9
	v_pk_mul_f32 v[10:11], v[172:173], v[10:11] op_sel_hi:[0,1]
	v_pk_mul_f32 v[10:11], v[36:37], v[10:11]
	v_add_u32_e32 v173, 0xd800, v177
	v_cvt_pk_bf16_f32 v9, v10, v11
	ds_write_b128 v177, v[6:9] offset:46080
	v_lshlrev_b32_e32 v6, 16, v2
	v_and_b32_e32 v7, 0xffff0000, v2
	v_pk_mul_f32 v[6:7], v[0:1], v[6:7] op_sel_hi:[0,1]
	v_pk_mul_f32 v[6:7], v[38:39], v[6:7]
	s_nop 0
	v_cvt_pk_bf16_f32 v2, v6, v7
	v_lshlrev_b32_e32 v6, 16, v3
	v_and_b32_e32 v7, 0xffff0000, v3
	v_pk_mul_f32 v[6:7], v[0:1], v[6:7] op_sel_hi:[0,1]
	v_pk_mul_f32 v[6:7], v[40:41], v[6:7]
	s_nop 0
	v_cvt_pk_bf16_f32 v3, v6, v7
	v_lshlrev_b32_e32 v6, 16, v4
	v_and_b32_e32 v7, 0xffff0000, v4
	v_pk_mul_f32 v[6:7], v[0:1], v[6:7] op_sel_hi:[0,1]
	v_pk_mul_f32 v[6:7], v[34:35], v[6:7]
	s_nop 0
	v_cvt_pk_bf16_f32 v4, v6, v7
	v_lshlrev_b32_e32 v6, 16, v5
	v_and_b32_e32 v7, 0xffff0000, v5
	v_pk_mul_f32 v[6:7], v[0:1], v[6:7] op_sel_hi:[0,1]
	v_pk_mul_f32 v[6:7], v[36:37], v[6:7]
	s_nop 0
	v_cvt_pk_bf16_f32 v5, v6, v7
	ds_write_b128 v177, v[2:5] offset:50688
	s_waitcnt vmcnt(19)
	ds_write_b128 v177, v[18:21] offset:55296
	s_waitcnt vmcnt(18)
	ds_write_b128 v177, v[22:25] offset:59904
	s_waitcnt vmcnt(17)
	ds_write_b128 v177, v[26:29] offset:64512
	s_waitcnt vmcnt(16)
	ds_write_b128 v173, v[30:33] offset:13824
	global_load_dwordx4 v[138:141], v[178:179], off offset:384
	global_load_dwordx4 v[158:161], v[180:181], off offset:384
	global_load_dwordx4 v[162:165], v[182:183], off offset:384
	global_load_dwordx4 v[166:169], v[184:185], off offset:384
	global_load_dwordx4 v[86:89], v[186:187], off offset:512
	global_load_dwordx4 v[82:85], v[188:189], off offset:512
	global_load_dwordx4 v[78:81], v[190:191], off offset:512
	global_load_dwordx4 v[70:73], v[192:193], off offset:512
	global_load_dwordx4 v[66:69], v211, s[48:49] offset:1040
	global_load_dwordx4 v[74:77], v211, s[48:49] offset:1024
	s_setprio 2
	v_lshrrev_b32_e32 v3, 1, v62
	v_mul_lo_u32 v2, v43, s34
	v_and_b32_e32 v3, 16, v3
	v_add3_u32 v175, 16, v2, v3
	v_lshlrev_b32_e32 v2, 1, v42
	v_add3_u32 v212, 16, v2, v3
	ds_read_b128 v[2:5], v175
	ds_read_b128 v[214:217], v175 offset:32
	ds_read_b128 v[6:9], v175 offset:4608
	ds_read_b128 v[218:221], v175 offset:4640
	ds_read_b128 v[10:13], v212 offset:18432
	ds_read_b128 v[222:225], v212 offset:18464
	ds_read_b128 v[14:17], v212 offset:23040
	ds_read_b128 v[226:229], v212 offset:23072
	s_waitcnt lgkmcnt(3)
	v_mfma_f32_32x32x16_bf16 v[50:65], v[2:5], v[10:13], 0
	s_waitcnt lgkmcnt(1)
	v_mfma_f32_32x32x16_bf16 v[34:49], v[2:5], v[14:17], 0
	v_mfma_f32_32x32x16_bf16 v[18:33], v[6:9], v[10:13], 0
	v_mfma_f32_32x32x16_bf16 v[2:17], v[6:9], v[14:17], 0
	ds_read_b128 v[230:233], v175 offset:64
	ds_read_b128 v[234:237], v175 offset:4672
	ds_read_b128 v[238:241], v212 offset:18496
	ds_read_b128 v[242:245], v212 offset:23104
	v_mfma_f32_32x32x16_bf16 v[50:65], v[214:217], v[222:225], v[50:65]
	s_waitcnt lgkmcnt(4)
	v_mfma_f32_32x32x16_bf16 v[34:49], v[214:217], v[226:229], v[34:49]
	v_mfma_f32_32x32x16_bf16 v[18:33], v[218:221], v[222:225], v[18:33]
	v_mfma_f32_32x32x16_bf16 v[2:17], v[218:221], v[226:229], v[2:17]
	ds_read_b128 v[214:217], v175 offset:96
	ds_read_b128 v[218:221], v175 offset:4704
	ds_read_b128 v[222:225], v212 offset:18528
	ds_read_b128 v[226:229], v212 offset:23136
	s_waitcnt lgkmcnt(5)
	v_mfma_f32_32x32x16_bf16 v[50:65], v[230:233], v[238:241], v[50:65]
	s_waitcnt lgkmcnt(4)
	v_mfma_f32_32x32x16_bf16 v[34:49], v[230:233], v[242:245], v[34:49]
	v_mfma_f32_32x32x16_bf16 v[18:33], v[234:237], v[238:241], v[18:33]
	v_mfma_f32_32x32x16_bf16 v[2:17], v[234:237], v[242:245], v[2:17]
	s_waitcnt lgkmcnt(1)
	v_mfma_f32_32x32x16_bf16 v[50:65], v[214:217], v[222:225], v[50:65]
	s_waitcnt lgkmcnt(0)
	v_mfma_f32_32x32x16_bf16 v[34:49], v[214:217], v[226:229], v[34:49]
	v_mfma_f32_32x32x16_bf16 v[18:33], v[218:221], v[222:225], v[18:33]
	v_mfma_f32_32x32x16_bf16 v[2:17], v[218:221], v[226:229], v[2:17]
	s_setprio 0
	s_waitcnt vmcnt(25)
	v_lshlrev_b32_e32 v214, 16, v134
	v_and_b32_e32 v215, 0xffff0000, v134
	v_mul_f32_e64 v214, v174, v214
	v_mul_f32_e64 v215, v174, v215
	s_waitcnt vmcnt(20)
	v_pk_mul_f32 v[214:215], v[214:215], v[130:131]
	s_nop 0
	v_cvt_pk_bf16_f32 v134, v214, v215
	v_lshlrev_b32_e32 v214, 16, v135
	v_and_b32_e32 v215, 0xffff0000, v135
	v_pk_mul_f32 v[214:215], v[174:175], v[214:215] op_sel_hi:[0,1]
	v_pk_mul_f32 v[214:215], v[214:215], v[132:133]
	s_barrier
	v_cvt_pk_bf16_f32 v135, v214, v215
	v_lshlrev_b32_e32 v214, 16, v136
	v_and_b32_e32 v215, 0xffff0000, v136
	v_pk_mul_f32 v[214:215], v[174:175], v[214:215] op_sel_hi:[0,1]
	v_pk_mul_f32 v[214:215], v[214:215], v[118:119]
	s_nop 0
	v_cvt_pk_bf16_f32 v136, v214, v215
	v_lshlrev_b32_e32 v214, 16, v137
	v_and_b32_e32 v215, 0xffff0000, v137
	v_pk_mul_f32 v[214:215], v[174:175], v[214:215] op_sel_hi:[0,1]
	v_pk_mul_f32 v[214:215], v[214:215], v[120:121]
	s_nop 0
	v_cvt_pk_bf16_f32 v137, v214, v215
	ds_write_b128 v177, v[134:137]
	v_lshlrev_b32_e32 v134, 16, v122
	v_and_b32_e32 v135, 0xffff0000, v122
	v_pk_mul_f32 v[134:135], v[176:177], v[134:135] op_sel_hi:[0,1]
	v_pk_mul_f32 v[134:135], v[130:131], v[134:135]
	s_nop 0
	v_cvt_pk_bf16_f32 v122, v134, v135
	v_lshlrev_b32_e32 v134, 16, v123
	v_and_b32_e32 v135, 0xffff0000, v123
	v_pk_mul_f32 v[134:135], v[176:177], v[134:135] op_sel_hi:[0,1]
	v_pk_mul_f32 v[134:135], v[132:133], v[134:135]
	s_nop 0
	v_cvt_pk_bf16_f32 v123, v134, v135
	v_lshlrev_b32_e32 v134, 16, v124
	v_and_b32_e32 v135, 0xffff0000, v124
	v_pk_mul_f32 v[134:135], v[176:177], v[134:135] op_sel_hi:[0,1]
	v_pk_mul_f32 v[134:135], v[134:135], v[118:119]
	s_nop 0
	v_cvt_pk_bf16_f32 v124, v134, v135
	v_lshlrev_b32_e32 v134, 16, v125
	v_and_b32_e32 v135, 0xffff0000, v125
	v_pk_mul_f32 v[134:135], v[176:177], v[134:135] op_sel_hi:[0,1]
	v_pk_mul_f32 v[134:135], v[134:135], v[120:121]
	s_nop 0
	v_cvt_pk_bf16_f32 v125, v134, v135
	ds_write_b128 v177, v[122:125] offset:4608
	v_lshlrev_b32_e32 v122, 16, v106
	v_and_b32_e32 v123, 0xffff0000, v106
	v_pk_mul_f32 v[122:123], v[172:173], v[122:123] op_sel_hi:[0,1]
	v_pk_mul_f32 v[122:123], v[130:131], v[122:123]
	s_nop 0
	v_cvt_pk_bf16_f32 v106, v122, v123
	v_lshlrev_b32_e32 v122, 16, v107
	v_and_b32_e32 v123, 0xffff0000, v107
	v_pk_mul_f32 v[122:123], v[172:173], v[122:123] op_sel_hi:[0,1]
	v_pk_mul_f32 v[122:123], v[132:133], v[122:123]
	s_nop 0
	v_cvt_pk_bf16_f32 v107, v122, v123
	v_lshlrev_b32_e32 v122, 16, v108
	v_and_b32_e32 v123, 0xffff0000, v108
	v_pk_mul_f32 v[122:123], v[172:173], v[122:123] op_sel_hi:[0,1]
	v_pk_mul_f32 v[122:123], v[118:119], v[122:123]
	s_nop 0
	v_cvt_pk_bf16_f32 v108, v122, v123
	v_lshlrev_b32_e32 v122, 16, v109
	v_and_b32_e32 v123, 0xffff0000, v109
	v_pk_mul_f32 v[122:123], v[172:173], v[122:123] op_sel_hi:[0,1]
	v_pk_mul_f32 v[122:123], v[120:121], v[122:123]
	s_nop 0
	v_cvt_pk_bf16_f32 v109, v122, v123
	ds_write_b128 v177, v[106:109] offset:9216
	v_lshlrev_b32_e32 v106, 16, v102
	v_and_b32_e32 v107, 0xffff0000, v102
	v_pk_mul_f32 v[106:107], v[0:1], v[106:107] op_sel_hi:[0,1]
	v_pk_mul_f32 v[106:107], v[130:131], v[106:107]
	s_nop 0
	v_cvt_pk_bf16_f32 v102, v106, v107
	v_lshlrev_b32_e32 v106, 16, v103
	v_and_b32_e32 v107, 0xffff0000, v103
	v_pk_mul_f32 v[106:107], v[0:1], v[106:107] op_sel_hi:[0,1]
	v_pk_mul_f32 v[106:107], v[132:133], v[106:107]
	s_nop 0
	v_cvt_pk_bf16_f32 v103, v106, v107
	v_lshlrev_b32_e32 v106, 16, v104
	v_and_b32_e32 v107, 0xffff0000, v104
	v_pk_mul_f32 v[106:107], v[0:1], v[106:107] op_sel_hi:[0,1]
	v_pk_mul_f32 v[106:107], v[118:119], v[106:107]
	s_nop 0
	v_cvt_pk_bf16_f32 v104, v106, v107
	v_lshlrev_b32_e32 v106, 16, v105
	v_and_b32_e32 v107, 0xffff0000, v105
	v_pk_mul_f32 v[106:107], v[0:1], v[106:107] op_sel_hi:[0,1]
	v_pk_mul_f32 v[106:107], v[120:121], v[106:107]
	s_nop 0
	v_cvt_pk_bf16_f32 v105, v106, v107
	ds_write_b128 v177, v[102:105] offset:13824
	s_waitcnt vmcnt(19)
	ds_write_b128 v177, v[142:145] offset:18432
	s_waitcnt vmcnt(18)
	ds_write_b128 v177, v[146:149] offset:23040
	s_waitcnt vmcnt(17)
	ds_write_b128 v177, v[150:153] offset:27648
	s_waitcnt vmcnt(16)
	ds_write_b128 v177, v[154:157] offset:32256
	global_load_dwordx4 v[102:105], v[178:179], off offset:512
	global_load_dwordx4 v[146:149], v[180:181], off offset:512
	global_load_dwordx4 v[150:153], v[182:183], off offset:512
	global_load_dwordx4 v[154:157], v[184:185], off offset:512
	global_load_dwordx4 v[142:145], v[186:187], off offset:640
	global_load_dwordx4 v[134:137], v[188:189], off offset:640
	global_load_dwordx4 v[130:133], v[190:191], off offset:640
	global_load_dwordx4 v[118:121], v[192:193], off offset:640
	global_load_dwordx4 v[106:109], v211, s[48:49] offset:1296
	global_load_dwordx4 v[122:125], v211, s[48:49] offset:1280
	s_setprio 2
	ds_read_b128 v[186:189], v175 offset:36864
	ds_read_b128 v[190:193], v175 offset:36896
	ds_read_b128 v[214:217], v175 offset:41472
	ds_read_b128 v[218:221], v175 offset:41504
	ds_read_b128 v[222:225], v212 offset:55296
	ds_read_b128 v[226:229], v212 offset:55328
	ds_read_b128 v[230:233], v212 offset:59904
	ds_read_b128 v[234:237], v212 offset:59936
	s_waitcnt lgkmcnt(3)
	v_mfma_f32_32x32x16_bf16 v[50:65], v[186:189], v[222:225], v[50:65]
	s_waitcnt lgkmcnt(1)
	v_mfma_f32_32x32x16_bf16 v[34:49], v[186:189], v[230:233], v[34:49]
	v_mfma_f32_32x32x16_bf16 v[18:33], v[214:217], v[222:225], v[18:33]
	v_mfma_f32_32x32x16_bf16 v[2:17], v[214:217], v[230:233], v[2:17]
	ds_read_b128 v[186:189], v175 offset:36928
	ds_read_b128 v[214:217], v175 offset:41536
	ds_read_b128 v[222:225], v212 offset:55360
	ds_read_b128 v[230:233], v212 offset:59968
	v_mfma_f32_32x32x16_bf16 v[50:65], v[190:193], v[226:229], v[50:65]
	s_waitcnt lgkmcnt(4)
	v_mfma_f32_32x32x16_bf16 v[34:49], v[190:193], v[234:237], v[34:49]
	v_mfma_f32_32x32x16_bf16 v[18:33], v[218:221], v[226:229], v[18:33]
	v_mfma_f32_32x32x16_bf16 v[2:17], v[218:221], v[234:237], v[2:17]
	ds_read_b128 v[190:193], v175 offset:36960
	ds_read_b128 v[218:221], v175 offset:41568
	ds_read_b128 v[226:229], v212 offset:55392
	ds_read_b128 v[234:237], v212 offset:60000
	s_waitcnt lgkmcnt(5)
	v_mfma_f32_32x32x16_bf16 v[50:65], v[186:189], v[222:225], v[50:65]
	s_waitcnt lgkmcnt(4)
	v_mfma_f32_32x32x16_bf16 v[34:49], v[186:189], v[230:233], v[34:49]
	v_mfma_f32_32x32x16_bf16 v[18:33], v[214:217], v[222:225], v[18:33]
	v_mfma_f32_32x32x16_bf16 v[2:17], v[214:217], v[230:233], v[2:17]
	s_waitcnt lgkmcnt(1)
	v_mfma_f32_32x32x16_bf16 v[50:65], v[190:193], v[226:229], v[50:65]
	s_waitcnt lgkmcnt(0)
	v_mfma_f32_32x32x16_bf16 v[34:49], v[190:193], v[234:237], v[34:49]
	v_mfma_f32_32x32x16_bf16 v[18:33], v[218:221], v[226:229], v[18:33]
	v_mfma_f32_32x32x16_bf16 v[2:17], v[218:221], v[234:237], v[2:17]
	s_setprio 0
	s_waitcnt vmcnt(25)
	v_lshlrev_b32_e32 v186, 16, v90
	v_and_b32_e32 v187, 0xffff0000, v90
	v_mul_f32_e64 v186, v174, v186
	v_mul_f32_e64 v187, v174, v187
	s_waitcnt vmcnt(20)
	v_pk_mul_f32 v[186:187], v[186:187], v[126:127]
	s_nop 0
	v_cvt_pk_bf16_f32 v90, v186, v187
	v_lshlrev_b32_e32 v186, 16, v91
	v_and_b32_e32 v187, 0xffff0000, v91
	v_pk_mul_f32 v[186:187], v[174:175], v[186:187] op_sel_hi:[0,1]
	v_pk_mul_f32 v[186:187], v[186:187], v[128:129]
	s_barrier
	v_cvt_pk_bf16_f32 v91, v186, v187
	v_lshlrev_b32_e32 v186, 16, v92
	v_and_b32_e32 v187, 0xffff0000, v92
	v_pk_mul_f32 v[186:187], v[174:175], v[186:187] op_sel_hi:[0,1]
	v_pk_mul_f32 v[186:187], v[186:187], v[110:111]
	s_nop 0
	v_cvt_pk_bf16_f32 v92, v186, v187
	v_lshlrev_b32_e32 v186, 16, v93
	v_and_b32_e32 v187, 0xffff0000, v93
	v_pk_mul_f32 v[186:187], v[174:175], v[186:187] op_sel_hi:[0,1]
	v_pk_mul_f32 v[186:187], v[186:187], v[112:113]
	s_nop 0
	v_cvt_pk_bf16_f32 v93, v186, v187
	ds_write_b128 v177, v[90:93] offset:36864
	v_lshlrev_b32_e32 v90, 16, v94
	v_and_b32_e32 v91, 0xffff0000, v94
	v_lshlrev_b32_e32 v92, 16, v95
	v_and_b32_e32 v93, 0xffff0000, v95
	v_pk_mul_f32 v[90:91], v[176:177], v[90:91] op_sel_hi:[0,1]
	v_pk_mul_f32 v[92:93], v[176:177], v[92:93] op_sel_hi:[0,1]
	v_pk_mul_f32 v[90:91], v[126:127], v[90:91]
	v_pk_mul_f32 v[92:93], v[128:129], v[92:93]
	v_cvt_pk_bf16_f32 v90, v90, v91
	v_cvt_pk_bf16_f32 v91, v92, v93
	v_lshlrev_b32_e32 v92, 16, v96
	v_and_b32_e32 v93, 0xffff0000, v96
	v_lshlrev_b32_e32 v94, 16, v97
	v_and_b32_e32 v95, 0xffff0000, v97
	v_pk_mul_f32 v[92:93], v[176:177], v[92:93] op_sel_hi:[0,1]
	v_pk_mul_f32 v[94:95], v[176:177], v[94:95] op_sel_hi:[0,1]
	v_pk_mul_f32 v[92:93], v[92:93], v[110:111]
	v_pk_mul_f32 v[94:95], v[94:95], v[112:113]
	v_cvt_pk_bf16_f32 v92, v92, v93
	v_cvt_pk_bf16_f32 v93, v94, v95
	ds_write_b128 v177, v[90:93] offset:41472
	v_lshlrev_b32_e32 v90, 16, v98
	v_and_b32_e32 v91, 0xffff0000, v98
	v_lshlrev_b32_e32 v92, 16, v99
	v_and_b32_e32 v93, 0xffff0000, v99
	v_pk_mul_f32 v[90:91], v[172:173], v[90:91] op_sel_hi:[0,1]
	v_pk_mul_f32 v[92:93], v[172:173], v[92:93] op_sel_hi:[0,1]
	v_pk_mul_f32 v[90:91], v[126:127], v[90:91]
	v_pk_mul_f32 v[92:93], v[128:129], v[92:93]
	v_cvt_pk_bf16_f32 v90, v90, v91
	v_cvt_pk_bf16_f32 v91, v92, v93
	v_lshlrev_b32_e32 v92, 16, v100
	v_and_b32_e32 v93, 0xffff0000, v100
	v_lshlrev_b32_e32 v94, 16, v101
	v_and_b32_e32 v95, 0xffff0000, v101
	v_pk_mul_f32 v[92:93], v[172:173], v[92:93] op_sel_hi:[0,1]
	v_pk_mul_f32 v[94:95], v[172:173], v[94:95] op_sel_hi:[0,1]
	v_pk_mul_f32 v[92:93], v[110:111], v[92:93]
	v_pk_mul_f32 v[94:95], v[112:113], v[94:95]
	v_cvt_pk_bf16_f32 v92, v92, v93
	v_cvt_pk_bf16_f32 v93, v94, v95
	ds_write_b128 v177, v[90:93] offset:46080
	v_lshlrev_b32_e32 v90, 16, v114
	v_and_b32_e32 v91, 0xffff0000, v114
	v_lshlrev_b32_e32 v92, 16, v115
	v_and_b32_e32 v93, 0xffff0000, v115
	v_pk_mul_f32 v[90:91], v[0:1], v[90:91] op_sel_hi:[0,1]
	v_pk_mul_f32 v[92:93], v[0:1], v[92:93] op_sel_hi:[0,1]
	v_pk_mul_f32 v[90:91], v[126:127], v[90:91]
	v_pk_mul_f32 v[92:93], v[128:129], v[92:93]
	v_cvt_pk_bf16_f32 v90, v90, v91
	v_cvt_pk_bf16_f32 v91, v92, v93
	v_lshlrev_b32_e32 v92, 16, v116
	v_and_b32_e32 v93, 0xffff0000, v116
	v_lshlrev_b32_e32 v94, 16, v117
	v_and_b32_e32 v95, 0xffff0000, v117
	v_pk_mul_f32 v[92:93], v[0:1], v[92:93] op_sel_hi:[0,1]
	v_pk_mul_f32 v[94:95], v[0:1], v[94:95] op_sel_hi:[0,1]
	v_pk_mul_f32 v[92:93], v[110:111], v[92:93]
	v_pk_mul_f32 v[94:95], v[112:113], v[94:95]
	v_cvt_pk_bf16_f32 v92, v92, v93
	v_cvt_pk_bf16_f32 v93, v94, v95
	ds_write_b128 v177, v[90:93] offset:50688
	s_waitcnt vmcnt(19)
	ds_write_b128 v177, v[138:141] offset:55296
	s_waitcnt vmcnt(18)
	ds_write_b128 v177, v[158:161] offset:59904
	s_waitcnt vmcnt(17)
	ds_write_b128 v177, v[162:165] offset:64512
	s_waitcnt vmcnt(16)
	ds_write_b128 v173, v[166:169] offset:13824
	global_load_dwordx4 v[90:93], v[178:179], off offset:640
	global_load_dwordx4 v[94:97], v[180:181], off offset:640
	global_load_dwordx4 v[98:101], v[182:183], off offset:640
	global_load_dwordx4 v[110:113], v[184:185], off offset:640
	s_setprio 2
	ds_read_b128 v[114:117], v175
	ds_read_b128 v[126:129], v175 offset:32
	ds_read_b128 v[138:141], v175 offset:4608
	ds_read_b128 v[158:161], v175 offset:4640
	ds_read_b128 v[162:165], v212 offset:18432
	ds_read_b128 v[166:169], v212 offset:18464
	ds_read_b128 v[178:181], v212 offset:23040
	ds_read_b128 v[182:185], v212 offset:23072
	s_waitcnt lgkmcnt(3)
	v_mfma_f32_32x32x16_bf16 v[50:65], v[114:117], v[162:165], v[50:65]
	s_waitcnt lgkmcnt(1)
	v_mfma_f32_32x32x16_bf16 v[34:49], v[114:117], v[178:181], v[34:49]
	v_mfma_f32_32x32x16_bf16 v[18:33], v[138:141], v[162:165], v[18:33]
	v_mfma_f32_32x32x16_bf16 v[2:17], v[138:141], v[178:181], v[2:17]
	ds_read_b128 v[114:117], v175 offset:64
	ds_read_b128 v[138:141], v175 offset:4672
	ds_read_b128 v[162:165], v212 offset:18496
	ds_read_b128 v[178:181], v212 offset:23104
	v_mfma_f32_32x32x16_bf16 v[50:65], v[126:129], v[166:169], v[50:65]
	s_waitcnt lgkmcnt(4)
	v_mfma_f32_32x32x16_bf16 v[34:49], v[126:129], v[182:185], v[34:49]
	v_mfma_f32_32x32x16_bf16 v[18:33], v[158:161], v[166:169], v[18:33]
	v_mfma_f32_32x32x16_bf16 v[2:17], v[158:161], v[182:185], v[2:17]
	ds_read_b128 v[126:129], v175 offset:96
	ds_read_b128 v[158:161], v175 offset:4704
	ds_read_b128 v[166:169], v212 offset:18528
	ds_read_b128 v[182:185], v212 offset:23136
	s_waitcnt lgkmcnt(5)
	v_mfma_f32_32x32x16_bf16 v[50:65], v[114:117], v[162:165], v[50:65]
	s_waitcnt lgkmcnt(4)
	v_mfma_f32_32x32x16_bf16 v[34:49], v[114:117], v[178:181], v[34:49]
	v_mfma_f32_32x32x16_bf16 v[18:33], v[138:141], v[162:165], v[18:33]
	v_mfma_f32_32x32x16_bf16 v[2:17], v[138:141], v[178:181], v[2:17]
	s_waitcnt lgkmcnt(1)
	v_mfma_f32_32x32x16_bf16 v[50:65], v[126:129], v[166:169], v[50:65]
	s_waitcnt lgkmcnt(0)
	v_mfma_f32_32x32x16_bf16 v[34:49], v[126:129], v[182:185], v[34:49]
	v_mfma_f32_32x32x16_bf16 v[18:33], v[158:161], v[166:169], v[18:33]
	v_mfma_f32_32x32x16_bf16 v[2:17], v[158:161], v[182:185], v[2:17]
	s_setprio 0
	s_waitcnt vmcnt(19)
	v_lshlrev_b32_e32 v114, 16, v86
	v_and_b32_e32 v115, 0xffff0000, v86
	v_mul_f32_e64 v114, v174, v114
	v_mul_f32_e64 v115, v174, v115
	s_waitcnt vmcnt(14)
	v_pk_mul_f32 v[114:115], v[114:115], v[74:75]
	s_nop 0
	v_cvt_pk_bf16_f32 v86, v114, v115
	v_lshlrev_b32_e32 v114, 16, v87
	v_and_b32_e32 v115, 0xffff0000, v87
	v_pk_mul_f32 v[114:115], v[174:175], v[114:115] op_sel_hi:[0,1]
	v_pk_mul_f32 v[114:115], v[114:115], v[76:77]
	s_barrier
	v_cvt_pk_bf16_f32 v87, v114, v115
	v_lshlrev_b32_e32 v114, 16, v88
	v_and_b32_e32 v115, 0xffff0000, v88
	v_pk_mul_f32 v[114:115], v[174:175], v[114:115] op_sel_hi:[0,1]
	v_pk_mul_f32 v[114:115], v[114:115], v[66:67]
	s_nop 0
	v_cvt_pk_bf16_f32 v88, v114, v115
	v_lshlrev_b32_e32 v114, 16, v89
	v_and_b32_e32 v115, 0xffff0000, v89
	v_pk_mul_f32 v[114:115], v[174:175], v[114:115] op_sel_hi:[0,1]
	v_pk_mul_f32 v[114:115], v[114:115], v[68:69]
	s_nop 0
	v_cvt_pk_bf16_f32 v89, v114, v115
	ds_write_b128 v177, v[86:89]
	v_lshlrev_b32_e32 v86, 16, v82
	v_and_b32_e32 v87, 0xffff0000, v82
	v_pk_mul_f32 v[86:87], v[176:177], v[86:87] op_sel_hi:[0,1]
	v_pk_mul_f32 v[86:87], v[74:75], v[86:87]
	s_nop 0
	v_cvt_pk_bf16_f32 v82, v86, v87
	v_lshlrev_b32_e32 v86, 16, v83
	v_and_b32_e32 v87, 0xffff0000, v83
	v_pk_mul_f32 v[86:87], v[176:177], v[86:87] op_sel_hi:[0,1]
	v_pk_mul_f32 v[86:87], v[76:77], v[86:87]
	s_nop 0
	v_cvt_pk_bf16_f32 v83, v86, v87
	v_lshlrev_b32_e32 v86, 16, v84
	v_and_b32_e32 v87, 0xffff0000, v84
	v_pk_mul_f32 v[86:87], v[176:177], v[86:87] op_sel_hi:[0,1]
	v_pk_mul_f32 v[86:87], v[86:87], v[66:67]
	s_nop 0
	v_cvt_pk_bf16_f32 v84, v86, v87
	v_lshlrev_b32_e32 v86, 16, v85
	v_and_b32_e32 v87, 0xffff0000, v85
	v_pk_mul_f32 v[86:87], v[176:177], v[86:87] op_sel_hi:[0,1]
	v_pk_mul_f32 v[86:87], v[86:87], v[68:69]
	s_nop 0
	v_cvt_pk_bf16_f32 v85, v86, v87
	ds_write_b128 v177, v[82:85] offset:4608
	v_lshlrev_b32_e32 v82, 16, v78
	v_and_b32_e32 v83, 0xffff0000, v78
	v_pk_mul_f32 v[82:83], v[172:173], v[82:83] op_sel_hi:[0,1]
	v_pk_mul_f32 v[82:83], v[74:75], v[82:83]
	s_nop 0
	v_cvt_pk_bf16_f32 v78, v82, v83
	v_lshlrev_b32_e32 v82, 16, v79
	v_and_b32_e32 v83, 0xffff0000, v79
	v_pk_mul_f32 v[82:83], v[172:173], v[82:83] op_sel_hi:[0,1]
	v_pk_mul_f32 v[82:83], v[76:77], v[82:83]
	s_nop 0
	v_cvt_pk_bf16_f32 v79, v82, v83
	v_lshlrev_b32_e32 v82, 16, v80
	v_and_b32_e32 v83, 0xffff0000, v80
	v_pk_mul_f32 v[82:83], v[172:173], v[82:83] op_sel_hi:[0,1]
	v_pk_mul_f32 v[82:83], v[66:67], v[82:83]
	s_nop 0
	v_cvt_pk_bf16_f32 v80, v82, v83
	v_lshlrev_b32_e32 v82, 16, v81
	v_and_b32_e32 v83, 0xffff0000, v81
	v_pk_mul_f32 v[82:83], v[172:173], v[82:83] op_sel_hi:[0,1]
	v_pk_mul_f32 v[82:83], v[68:69], v[82:83]
	s_nop 0
	v_cvt_pk_bf16_f32 v81, v82, v83
	ds_write_b128 v177, v[78:81] offset:9216
	v_lshlrev_b32_e32 v78, 16, v70
	v_and_b32_e32 v79, 0xffff0000, v70
	v_pk_mul_f32 v[78:79], v[0:1], v[78:79] op_sel_hi:[0,1]
	v_pk_mul_f32 v[74:75], v[74:75], v[78:79]
	s_nop 0
	v_cvt_pk_bf16_f32 v70, v74, v75
	v_lshlrev_b32_e32 v74, 16, v71
	v_and_b32_e32 v75, 0xffff0000, v71
	v_pk_mul_f32 v[74:75], v[0:1], v[74:75] op_sel_hi:[0,1]
	v_pk_mul_f32 v[74:75], v[76:77], v[74:75]
	s_nop 0
	v_cvt_pk_bf16_f32 v71, v74, v75
	v_lshlrev_b32_e32 v74, 16, v72
	v_and_b32_e32 v75, 0xffff0000, v72
	v_pk_mul_f32 v[74:75], v[0:1], v[74:75] op_sel_hi:[0,1]
	v_pk_mul_f32 v[66:67], v[66:67], v[74:75]
	s_nop 0
	v_cvt_pk_bf16_f32 v72, v66, v67
	v_lshlrev_b32_e32 v66, 16, v73
	v_and_b32_e32 v67, 0xffff0000, v73
	v_pk_mul_f32 v[66:67], v[0:1], v[66:67] op_sel_hi:[0,1]
	v_pk_mul_f32 v[66:67], v[68:69], v[66:67]
	s_nop 0
	v_cvt_pk_bf16_f32 v73, v66, v67
	ds_write_b128 v177, v[70:73] offset:13824
	s_waitcnt vmcnt(13)
	ds_write_b128 v177, v[102:105] offset:18432
	s_waitcnt vmcnt(12)
	ds_write_b128 v177, v[146:149] offset:23040
	s_waitcnt vmcnt(11)
	ds_write_b128 v177, v[150:153] offset:27648
	s_waitcnt vmcnt(10)
	ds_write_b128 v177, v[154:157] offset:32256
	s_setprio 2
	ds_read_b128 v[66:69], v175 offset:36864
	ds_read_b128 v[70:73], v175 offset:36896
	ds_read_b128 v[74:77], v175 offset:41472
	ds_read_b128 v[78:81], v175 offset:41504
	ds_read_b128 v[82:85], v212 offset:55296
	ds_read_b128 v[86:89], v212 offset:55328
	ds_read_b128 v[102:105], v212 offset:59904
	ds_read_b128 v[114:117], v212 offset:59936
	s_waitcnt lgkmcnt(3)
	v_mfma_f32_32x32x16_bf16 v[50:65], v[66:69], v[82:85], v[50:65]
	s_waitcnt lgkmcnt(1)
	v_mfma_f32_32x32x16_bf16 v[34:49], v[66:69], v[102:105], v[34:49]
	v_mfma_f32_32x32x16_bf16 v[18:33], v[74:77], v[82:85], v[18:33]
	v_mfma_f32_32x32x16_bf16 v[2:17], v[74:77], v[102:105], v[2:17]
	ds_read_b128 v[66:69], v175 offset:36928
	ds_read_b128 v[74:77], v175 offset:41536
	ds_read_b128 v[82:85], v212 offset:55360
	ds_read_b128 v[102:105], v212 offset:59968
	v_mfma_f32_32x32x16_bf16 v[50:65], v[70:73], v[86:89], v[50:65]
	s_waitcnt lgkmcnt(4)
	v_mfma_f32_32x32x16_bf16 v[34:49], v[70:73], v[114:117], v[34:49]
	v_mfma_f32_32x32x16_bf16 v[18:33], v[78:81], v[86:89], v[18:33]
	v_mfma_f32_32x32x16_bf16 v[2:17], v[78:81], v[114:117], v[2:17]
	ds_read_b128 v[70:73], v175 offset:36960
	ds_read_b128 v[78:81], v175 offset:41568
	ds_read_b128 v[86:89], v212 offset:55392
	ds_read_b128 v[114:117], v212 offset:60000
	s_waitcnt lgkmcnt(5)
	v_mfma_f32_32x32x16_bf16 v[50:65], v[66:69], v[82:85], v[50:65]
	s_waitcnt lgkmcnt(4)
	v_mfma_f32_32x32x16_bf16 v[34:49], v[66:69], v[102:105], v[34:49]
	v_mfma_f32_32x32x16_bf16 v[18:33], v[74:77], v[82:85], v[18:33]
	v_mfma_f32_32x32x16_bf16 v[2:17], v[74:77], v[102:105], v[2:17]
	s_waitcnt lgkmcnt(1)
	v_mfma_f32_32x32x16_bf16 v[50:65], v[70:73], v[86:89], v[50:65]
	s_waitcnt lgkmcnt(0)
	v_mfma_f32_32x32x16_bf16 v[34:49], v[70:73], v[114:117], v[34:49]
	v_mfma_f32_32x32x16_bf16 v[18:33], v[78:81], v[86:89], v[18:33]
	v_mfma_f32_32x32x16_bf16 v[2:17], v[78:81], v[114:117], v[2:17]
	s_setprio 0
	s_waitcnt vmcnt(9)
	v_lshlrev_b32_e32 v66, 16, v142
	v_and_b32_e32 v67, 0xffff0000, v142
	v_lshlrev_b32_e32 v68, 16, v143
	v_and_b32_e32 v69, 0xffff0000, v143
	v_pk_mul_f32 v[66:67], v[174:175], v[66:67] op_sel_hi:[0,1]
	v_pk_mul_f32 v[68:69], v[174:175], v[68:69] op_sel_hi:[0,1]
	s_waitcnt vmcnt(4)
	v_pk_mul_f32 v[66:67], v[66:67], v[122:123]
	v_pk_mul_f32 v[68:69], v[68:69], v[124:125]
	v_cvt_pk_bf16_f32 v66, v66, v67
	v_cvt_pk_bf16_f32 v67, v68, v69
	v_lshlrev_b32_e32 v68, 16, v144
	v_and_b32_e32 v69, 0xffff0000, v144
	v_lshlrev_b32_e32 v70, 16, v145
	v_and_b32_e32 v71, 0xffff0000, v145
	v_pk_mul_f32 v[68:69], v[174:175], v[68:69] op_sel_hi:[0,1]
	v_pk_mul_f32 v[70:71], v[174:175], v[70:71] op_sel_hi:[0,1]
	v_pk_mul_f32 v[68:69], v[68:69], v[106:107]
	v_pk_mul_f32 v[70:71], v[70:71], v[108:109]
	v_cvt_pk_bf16_f32 v68, v68, v69
	v_cvt_pk_bf16_f32 v69, v70, v71
	s_barrier
	ds_write_b128 v177, v[66:69] offset:36864
	v_lshlrev_b32_e32 v66, 16, v134
	v_and_b32_e32 v67, 0xffff0000, v134
	v_lshlrev_b32_e32 v68, 16, v135
	v_and_b32_e32 v69, 0xffff0000, v135
	v_pk_mul_f32 v[66:67], v[176:177], v[66:67] op_sel_hi:[0,1]
	v_pk_mul_f32 v[68:69], v[176:177], v[68:69] op_sel_hi:[0,1]
	v_pk_mul_f32 v[66:67], v[122:123], v[66:67]
	v_pk_mul_f32 v[68:69], v[124:125], v[68:69]
	v_cvt_pk_bf16_f32 v66, v66, v67
	v_cvt_pk_bf16_f32 v67, v68, v69
	v_lshlrev_b32_e32 v68, 16, v136
	v_and_b32_e32 v69, 0xffff0000, v136
	v_lshlrev_b32_e32 v70, 16, v137
	v_and_b32_e32 v71, 0xffff0000, v137
	v_pk_mul_f32 v[68:69], v[176:177], v[68:69] op_sel_hi:[0,1]
	v_pk_mul_f32 v[70:71], v[176:177], v[70:71] op_sel_hi:[0,1]
	v_pk_mul_f32 v[68:69], v[68:69], v[106:107]
	v_pk_mul_f32 v[70:71], v[70:71], v[108:109]
	v_cvt_pk_bf16_f32 v68, v68, v69
	v_cvt_pk_bf16_f32 v69, v70, v71
	ds_write_b128 v177, v[66:69] offset:41472
	v_lshlrev_b32_e32 v66, 16, v130
	v_and_b32_e32 v67, 0xffff0000, v130
	v_lshlrev_b32_e32 v68, 16, v131
	v_and_b32_e32 v69, 0xffff0000, v131
	v_pk_mul_f32 v[66:67], v[172:173], v[66:67] op_sel_hi:[0,1]
	v_pk_mul_f32 v[68:69], v[172:173], v[68:69] op_sel_hi:[0,1]
	v_pk_mul_f32 v[66:67], v[122:123], v[66:67]
	v_pk_mul_f32 v[68:69], v[124:125], v[68:69]
	v_cvt_pk_bf16_f32 v66, v66, v67
	v_cvt_pk_bf16_f32 v67, v68, v69
	v_lshlrev_b32_e32 v68, 16, v132
	v_and_b32_e32 v69, 0xffff0000, v132
	v_lshlrev_b32_e32 v70, 16, v133
	v_and_b32_e32 v71, 0xffff0000, v133
	v_pk_mul_f32 v[68:69], v[172:173], v[68:69] op_sel_hi:[0,1]
	v_pk_mul_f32 v[70:71], v[172:173], v[70:71] op_sel_hi:[0,1]
	v_pk_mul_f32 v[68:69], v[106:107], v[68:69]
	v_pk_mul_f32 v[70:71], v[108:109], v[70:71]
	v_cvt_pk_bf16_f32 v68, v68, v69
	v_cvt_pk_bf16_f32 v69, v70, v71
	ds_write_b128 v177, v[66:69] offset:46080
	v_lshlrev_b32_e32 v66, 16, v118
	v_and_b32_e32 v67, 0xffff0000, v118
	v_lshlrev_b32_e32 v68, 16, v119
	v_and_b32_e32 v69, 0xffff0000, v119
	v_pk_mul_f32 v[66:67], v[0:1], v[66:67] op_sel_hi:[0,1]
	v_pk_mul_f32 v[68:69], v[0:1], v[68:69] op_sel_hi:[0,1]
	v_pk_mul_f32 v[66:67], v[122:123], v[66:67]
	v_pk_mul_f32 v[68:69], v[124:125], v[68:69]
	v_cvt_pk_bf16_f32 v66, v66, v67
	v_cvt_pk_bf16_f32 v67, v68, v69
	v_lshlrev_b32_e32 v68, 16, v120
	v_and_b32_e32 v69, 0xffff0000, v120
	v_lshlrev_b32_e32 v70, 16, v121
	v_and_b32_e32 v71, 0xffff0000, v121
	v_pk_mul_f32 v[68:69], v[0:1], v[68:69] op_sel_hi:[0,1]
	v_pk_mul_f32 v[70:71], v[0:1], v[70:71] op_sel_hi:[0,1]
	v_pk_mul_f32 v[68:69], v[106:107], v[68:69]
	v_pk_mul_f32 v[70:71], v[108:109], v[70:71]
	v_cvt_pk_bf16_f32 v68, v68, v69
	v_cvt_pk_bf16_f32 v69, v70, v71
	ds_write_b128 v177, v[66:69] offset:50688
	s_waitcnt vmcnt(3)
	ds_write_b128 v177, v[90:93] offset:55296
	s_waitcnt vmcnt(2)
	ds_write_b128 v177, v[94:97] offset:59904
	s_waitcnt vmcnt(1)
	ds_write_b128 v177, v[98:101] offset:64512
	s_waitcnt vmcnt(0)
	ds_write_b128 v173, v[110:113] offset:13824
	s_setprio 2
	ds_read_b128 v[66:69], v175
	ds_read_b128 v[70:73], v175 offset:32
	ds_read_b128 v[74:77], v175 offset:4608
	ds_read_b128 v[78:81], v175 offset:4640
	ds_read_b128 v[82:85], v212 offset:18432
	ds_read_b128 v[86:89], v212 offset:18464
	ds_read_b128 v[90:93], v212 offset:23040
	ds_read_b128 v[94:97], v212 offset:23072
	s_waitcnt lgkmcnt(3)
	v_mfma_f32_32x32x16_bf16 v[50:65], v[66:69], v[82:85], v[50:65]
	s_waitcnt lgkmcnt(1)
	v_mfma_f32_32x32x16_bf16 v[34:49], v[66:69], v[90:93], v[34:49]
	v_mfma_f32_32x32x16_bf16 v[18:33], v[74:77], v[82:85], v[18:33]
	v_mfma_f32_32x32x16_bf16 v[2:17], v[74:77], v[90:93], v[2:17]
	ds_read_b128 v[66:69], v175 offset:64
	ds_read_b128 v[74:77], v175 offset:4672
	ds_read_b128 v[82:85], v212 offset:18496
	ds_read_b128 v[90:93], v212 offset:23104
	v_mfma_f32_32x32x16_bf16 v[50:65], v[70:73], v[86:89], v[50:65]
	s_waitcnt lgkmcnt(4)
	v_mfma_f32_32x32x16_bf16 v[34:49], v[70:73], v[94:97], v[34:49]
	v_mfma_f32_32x32x16_bf16 v[18:33], v[78:81], v[86:89], v[18:33]
	v_mfma_f32_32x32x16_bf16 v[2:17], v[78:81], v[94:97], v[2:17]
	ds_read_b128 v[70:73], v175 offset:96
	ds_read_b128 v[78:81], v175 offset:4704
	ds_read_b128 v[86:89], v212 offset:18528
	ds_read_b128 v[94:97], v212 offset:23136
	s_waitcnt lgkmcnt(5)
	v_mfma_f32_32x32x16_bf16 v[50:65], v[66:69], v[82:85], v[50:65]
	s_waitcnt lgkmcnt(4)
	v_mfma_f32_32x32x16_bf16 v[34:49], v[66:69], v[90:93], v[34:49]
	v_mfma_f32_32x32x16_bf16 v[18:33], v[74:77], v[82:85], v[18:33]
	v_mfma_f32_32x32x16_bf16 v[2:17], v[74:77], v[90:93], v[2:17]
	s_waitcnt lgkmcnt(1)
	v_mfma_f32_32x32x16_bf16 v[50:65], v[70:73], v[86:89], v[50:65]
	s_waitcnt lgkmcnt(0)
	v_mfma_f32_32x32x16_bf16 v[34:49], v[70:73], v[94:97], v[34:49]
	v_mfma_f32_32x32x16_bf16 v[18:33], v[78:81], v[86:89], v[18:33]
	v_mfma_f32_32x32x16_bf16 v[2:17], v[78:81], v[94:97], v[2:17]
	s_setprio 0
	s_barrier
	s_setprio 2
	ds_read_b128 v[66:69], v175 offset:36864
	ds_read_b128 v[70:73], v175 offset:36896
	ds_read_b128 v[74:77], v175 offset:41472
	ds_read_b128 v[78:81], v175 offset:41504
	ds_read_b128 v[82:85], v212 offset:55296
	ds_read_b128 v[86:89], v212 offset:55328
	ds_read_b128 v[90:93], v212 offset:59904
	ds_read_b128 v[94:97], v212 offset:59936
	s_waitcnt lgkmcnt(3)
	v_mfma_f32_32x32x16_bf16 v[50:65], v[66:69], v[82:85], v[50:65]
	s_waitcnt lgkmcnt(1)
	v_mfma_f32_32x32x16_bf16 v[34:49], v[66:69], v[90:93], v[34:49]
	v_mfma_f32_32x32x16_bf16 v[18:33], v[74:77], v[82:85], v[18:33]
	v_mfma_f32_32x32x16_bf16 v[2:17], v[74:77], v[90:93], v[2:17]
	ds_read_b128 v[66:69], v175 offset:36928
	ds_read_b128 v[74:77], v175 offset:41536
	ds_read_b128 v[82:85], v212 offset:55360
	ds_read_b128 v[90:93], v212 offset:59968
	v_mfma_f32_32x32x16_bf16 v[50:65], v[70:73], v[86:89], v[50:65]
	s_waitcnt lgkmcnt(4)
	v_mfma_f32_32x32x16_bf16 v[34:49], v[70:73], v[94:97], v[34:49]
	v_mfma_f32_32x32x16_bf16 v[18:33], v[78:81], v[86:89], v[18:33]
	v_mfma_f32_32x32x16_bf16 v[2:17], v[78:81], v[94:97], v[2:17]
	ds_read_b128 v[70:73], v175 offset:36960
	ds_read_b128 v[78:81], v175 offset:41568
	ds_read_b128 v[86:89], v212 offset:55392
	ds_read_b128 v[94:97], v212 offset:60000
	s_waitcnt lgkmcnt(5)
	v_mfma_f32_32x32x16_bf16 v[50:65], v[66:69], v[82:85], v[50:65]
	s_waitcnt lgkmcnt(4)
	v_mfma_f32_32x32x16_bf16 v[34:49], v[66:69], v[90:93], v[34:49]
	v_mfma_f32_32x32x16_bf16 v[18:33], v[74:77], v[82:85], v[18:33]
	v_mfma_f32_32x32x16_bf16 v[2:17], v[74:77], v[90:93], v[2:17]
	s_waitcnt lgkmcnt(1)
	v_mfma_f32_32x32x16_bf16 v[50:65], v[70:73], v[86:89], v[50:65]
	s_waitcnt lgkmcnt(0)
	v_mfma_f32_32x32x16_bf16 v[34:49], v[70:73], v[94:97], v[34:49]
	v_mfma_f32_32x32x16_bf16 v[18:33], v[78:81], v[86:89], v[18:33]
	v_mfma_f32_32x32x16_bf16 v[2:17], v[78:81], v[94:97], v[2:17]
	s_setprio 0
	s_barrier
	v_mov_b32 v0, v194
	s_mov_b64 s[10:11], -1
	v_ashrrev_i32_e32 v66, 7, v0
	v_and_b32_e32 v102, 31, v0
	v_bfe_u32 v103, v0, 5, 1
	v_bfe_u32 v104, v0, 6, 1
	s_cmp_gt_u32 s8, 15
	v_lshl_add_u32 v105, v66, 6, s12
	s_cbranch_scc0 .LBB0_1285
	v_and_b32_e32 v66, 7, v0
	v_cvt_f32_ubyte0_e32 v66, v66
	v_mul_f32_e32 v67, 0xbfd49a78, v66
	s_mov_b32 s6, 0xc2fc0000
	v_cmp_gt_f32_e32 vcc, s6, v67
	v_and_b32_e32 v0, 8, v0
	s_cmp_gt_u32 s9, 31
	v_cndmask_b32_e32 v67, 0, v205, vcc
	v_fmac_f32_e32 v67, 0xbfd49a78, v66
	v_exp_f32_e32 v66, v67
	v_cndmask_b32_e32 v67, 0, v206, vcc
	v_cmp_eq_u32_e64 s[40:41], 0, v0
	v_lshlrev_b32_e32 v0, 2, v103
	v_bfe_u32 v108, v105, 6, 5
	v_xor_b32_e32 v106, 8, v200
	v_cmp_gt_u32_e64 s[44:45], 16, v102
	s_cselect_b64 s[10:11], -1, 0
	s_cmp_lt_u32 s9, 32
	v_ldexp_f32 v107, v66, v67
	v_cndmask_b32_e64 v70, v0, v108, s[44:45]
	v_cmp_lt_i32_e32 vcc, v106, v171
	v_mov_b32_e32 v67, v50
	s_cbranch_scc1 .LBB0_1158
	v_cvt_f32_ubyte0_e32 v66, v70
	v_cndmask_b32_e32 v68, v200, v106, vcc
	v_mul_f32_e32 v66, v107, v66
	v_lshlrev_b32_e32 v68, 2, v68
	v_mul_f32_e32 v67, 0.15915494, v66
	ds_bpermute_b32 v68, v68, v50
	v_floor_f32_e32 v67, v67
	v_fma_f32 v66, v66, 0.15915494, -v67
	v_sin_f32_e32 v67, v66
	v_cos_f32_e32 v66, v66
	s_nop 1
	s_waitcnt lgkmcnt(0)
	v_mul_f32_e32 v67, v67, v68
	v_cndmask_b32_e64 v67, v67, -v67, s[40:41]
	v_fmac_f32_e32 v67, v50, v66
